# v42 + s5c item: the 16 KB Toeplitz fragment image (identical for all 8 waves) is loaded once per workgroup (2 fragments per wave) and shared through free LDS instead of 16 loads per wave
# baseline (speedup 1.0000x reference)
; #define LAS __attribute__((address_space(3)))
; __device__ __forceinline__ u32x4 pack8(const f32x4 a, const f32x4 b) { u32x4 w; w.x = cvt_pk_bf16(a[0], a[1]); w.y = cvt_pk_bf16(a[2], a[3]); w.z = cvt_pk_bf16(b[0], b[1]); w.w = cvt_pk_bf16(b[2], b[3]); return w; }
; __device__ void s5c_item(const Params& p, int l, int item, LAS unsigned char* lds) {
;     ...
;     for (int it = 0; it < iters; ++it) {
;         const int mt = mt0 + it * 8 + wave; const bool active = mt < mt0 + nmt;
;         u32x4 omf[8];
; #pragma unroll
;         for (int q = 0; q < 8; ++q) { const int i = t + 512 * q, r = i >> 4, c = i & 15; omf[q] = *(const u32x4*)(Wy + (size_t)r * 384 + 256 + c * 8); }
;         bf16x8 tf[16];
; #pragma unroll
;         for (int d = 0; d < 16; ++d) tf[d] = *(const bf16x8*)(Tz + d * 512 + fr * 32 + fq * 8);
;         bf16x8 a[12];
;         if (active) {
; #pragma unroll
;             for (int ks = 0; ks < 8; ++ks) a[ks] = *(const bf16x8*)(proj + (size_t)((mt * 16 + fr) * 16 + 2 * ks + (fq >> 1)) * NPROJ + C_U + g * 16 + (fq & 1) * 8);
; #pragma unroll
;             for (int kk = 0; kk < 4; ++kk) { const float* xp = Xin + ((size_t)(mt * 16 + fr) * 32 + g) * 128 + kk * 32 + fq * 8; const f32x4 x0 = *(const f32x4*)xp, x1 = *(const f32x4*)(xp + 4);
;                 const u32x4 w = pack8(x0, x1); a[8 + kk] = *(const bf16x8*)&w; }
;         } else {
; #pragma unroll
;             for (int ks = 0; ks < 12; ++ks) a[ks] = (bf16x8){0, 0, 0, 0, 0, 0, 0, 0};
;         }
;         __syncthreads();
; #pragma unroll
;         for (int q = 0; q < 8; ++q) { const int i = t + 512 * q, r = i >> 4, c = i & 15; *(LAS u32x4*)(lds + r * 272 + c * 16) = omf[q]; }
.LBB0_526:
	global_load_dwordx4 v[118:121], v[158:159], off
	global_load_dwordx4 v[122:125], v[160:161], off
	global_load_dwordx4 v[126:129], v[162:163], off
	global_load_dwordx4 v[130:133], v[164:165], off
	global_load_dwordx4 v[134:137], v[166:167], off
	global_load_dwordx4 v[138:141], v[168:169], off
	global_load_dwordx4 v[142:145], v[170:171], off
	global_load_dwordx4 v[146:149], v[172:173], off
	v_bfe_u32 v78, v228, 6, 3
	v_lshlrev_b32_e32 v78, 11, v78
	s_nop 0
	v_readfirstlane_b32 s100, v78
	s_mov_b32 s101, 0
	s_nop 1
	v_lshl_add_u64 v[6:7], v[150:151], 0, s[100:101]
	global_load_dwordx4 v[74:77], v[6:7], off
	s_nop 0
	global_load_dwordx4 v[6:9], v[6:7], off offset:1024
	v_cmp_gt_i32_e32 vcc, s30, v208
	s_waitcnt vmcnt(10)
	v_mov_b32_e32 v206, 0
	v_mov_b32_e32 v114, 0
	v_mov_b32_e32 v115, 0
	v_mov_b32_e32 v116, 0
	v_mov_b32_e32 v117, 0
	v_mov_b32_e32 v110, 0
	v_mov_b32_e32 v111, 0
	v_mov_b32_e32 v112, 0
	v_mov_b32_e32 v113, 0
	v_mov_b32_e32 v98, 0
	v_mov_b32_e32 v99, 0
	v_mov_b32_e32 v100, 0
	v_mov_b32_e32 v101, 0
	v_mov_b32_e32 v70, 0
	v_mov_b32_e32 v71, 0
	v_mov_b32_e32 v72, 0
	v_mov_b32_e32 v73, 0
	v_mov_b32_e32 v38, 0
	v_mov_b32_e32 v39, 0
	v_mov_b32_e32 v40, 0
	v_mov_b32_e32 v41, 0
	v_mov_b32_e32 v50, 0
	v_mov_b32_e32 v51, 0
	v_mov_b32_e32 v52, 0
	v_mov_b32_e32 v53, 0
	v_mov_b32_e32 v62, 0
	v_mov_b32_e32 v63, 0
	v_mov_b32_e32 v64, 0
	v_mov_b32_e32 v65, 0
	v_mov_b32_e32 v54, 0
	v_mov_b32_e32 v55, 0
	v_mov_b32_e32 v56, 0
	v_mov_b32_e32 v57, 0
	v_mov_b32_e32 v66, 0
	v_mov_b32_e32 v67, 0
	v_mov_b32_e32 v68, 0
	v_mov_b32_e32 v69, 0
	v_mov_b32_e32 v46, 0
	v_mov_b32_e32 v47, 0
	v_mov_b32_e32 v48, 0
	v_mov_b32_e32 v49, 0
	v_mov_b32_e32 v58, 0
	v_mov_b32_e32 v59, 0
	v_mov_b32_e32 v60, 0
	v_mov_b32_e32 v61, 0
	v_mov_b32_e32 v42, 0
	v_mov_b32_e32 v43, 0
	v_mov_b32_e32 v44, 0
	v_mov_b32_e32 v45, 0
	s_and_saveexec_b64 s[10:11], vcc
	s_cbranch_execz .LBB0_528
	v_add_u32_e32 v40, s41, v210
	v_mad_i64_i32 v[38:39], s[14:15], v40, s96, v[152:153]
	global_load_dwordx4 v[42:45], v[38:39], off
	v_add_u32_e32 v38, 2, v40
	v_mad_i64_i32 v[38:39], s[14:15], v38, s96, v[152:153]
	global_load_dwordx4 v[58:61], v[38:39], off
	v_add_u32_e32 v38, 4, v40
	v_mad_i64_i32 v[38:39], s[14:15], v38, s96, v[152:153]
	global_load_dwordx4 v[46:49], v[38:39], off
	v_add_u32_e32 v38, 6, v40
	v_mad_i64_i32 v[38:39], s[14:15], v38, s96, v[152:153]
	global_load_dwordx4 v[66:69], v[38:39], off
	v_add_u32_e32 v38, 8, v40
	v_mad_i64_i32 v[38:39], s[14:15], v38, s96, v[152:153]
	global_load_dwordx4 v[54:57], v[38:39], off
	v_add_u32_e32 v38, 10, v40
	v_mad_i64_i32 v[38:39], s[14:15], v38, s96, v[152:153]
	global_load_dwordx4 v[62:65], v[38:39], off
	v_add_u32_e32 v38, 12, v40
	v_mad_i64_i32 v[38:39], s[14:15], v38, s96, v[152:153]
	v_ashrrev_i32_e32 v205, 31, v204
	global_load_dwordx4 v[50:53], v[38:39], off
	v_add_u32_e32 v38, 14, v40
	v_lshlrev_b64 v[70:71], 14, v[204:205]
	v_mad_i64_i32 v[38:39], s[14:15], v38, s96, v[152:153]
	v_lshl_add_u64 v[116:117], v[154:155], 0, v[70:71]
	global_load_dwordx4 v[38:41], v[38:39], off
	s_nop 0
	global_load_dwordx4 v[98:101], v[116:117], off offset:16
	global_load_dwordx4 v[70:73], v[116:117], off
	s_waitcnt vmcnt(0)
	v_cvt_pk_bf16_f32 v70, v70, v71
	v_cvt_pk_bf16_f32 v71, v72, v73
	v_cvt_pk_bf16_f32 v72, v98, v99
	v_cvt_pk_bf16_f32 v73, v100, v101
	global_load_dwordx4 v[110:113], v[116:117], off offset:144
	global_load_dwordx4 v[98:101], v[116:117], off offset:128
	s_waitcnt vmcnt(0)
	v_cvt_pk_bf16_f32 v98, v98, v99
	v_cvt_pk_bf16_f32 v99, v100, v101
	v_cvt_pk_bf16_f32 v101, v112, v113
	global_load_dwordx4 v[112:115], v[116:117], off offset:272
	global_load_dwordx4 v[220:223], v[116:117], off offset:256
	v_cvt_pk_bf16_f32 v100, v110, v111
	s_waitcnt vmcnt(1)
	v_cvt_pk_bf16_f32 v112, v112, v113
	s_waitcnt vmcnt(0)
	v_cvt_pk_bf16_f32 v110, v220, v221
	v_cvt_pk_bf16_f32 v111, v222, v223
	v_cvt_pk_bf16_f32 v113, v114, v115
	global_load_dwordx4 v[220:223], v[116:117], off offset:400
	s_nop 0
	global_load_dwordx4 v[114:117], v[116:117], off offset:384
	s_waitcnt vmcnt(0)
	v_cvt_pk_bf16_f32 v114, v114, v115
	v_cvt_pk_bf16_f32 v115, v116, v117
	v_cvt_pk_bf16_f32 v116, v220, v221
	v_cvt_pk_bf16_f32 v117, v222, v223
.LBB0_528:
	s_or_b64 exec, exec, s[10:11]
	v_add_u32_e32 v242, s41, v209
	s_barrier
	s_waitcnt vmcnt(9)
	ds_write_b128 v211, v[118:121]
	s_waitcnt vmcnt(8)
	ds_write_b128 v212, v[122:125]
	s_waitcnt vmcnt(7)
	ds_write_b128 v213, v[126:129]
	s_waitcnt vmcnt(6)
	ds_write_b128 v214, v[130:133]
	s_waitcnt vmcnt(5)
	ds_write_b128 v215, v[134:137]
	s_waitcnt vmcnt(4)
	ds_write_b128 v216, v[138:141]
	s_waitcnt vmcnt(3)
	ds_write_b128 v217, v[142:145]
	s_waitcnt vmcnt(2)
	ds_write_b128 v218, v[146:149]
	s_waitcnt vmcnt(0)
	v_and_b32_e32 v78, 63, v228
	v_lshlrev_b32_e32 v78, 4, v78
	v_add_u32_e32 v78, 0x11000, v78
	v_add_u32_e32 v79, s100, v78
	ds_write_b128 v79, v[74:77]
	ds_write_b128 v79, v[6:9] offset:1024
	v_add_u32_e32 v241, 1, v242
	v_add_u32_e32 v240, 2, v242
	v_add_u32_e32 v239, 3, v242
	v_add_u32_e32 v227, 4, v242
	v_add_u32_e32 v226, 5, v242
	v_add_u32_e32 v225, 6, v242
	v_add_u32_e32 v224, 7, v242
	v_add_u32_e32 v223, 8, v242
	v_add_u32_e32 v222, 9, v242
	v_add_u32_e32 v221, 10, v242
	v_add_u32_e32 v220, 11, v242
	v_add_u32_e32 v219, 12, v242
	v_add_u32_e32 v205, 13, v242
	v_add_u32_e32 v149, 14, v242
	v_add_u32_e32 v148, 15, v242
	v_mov_b32_e32 v207, 0
	v_mov_b32_e32 v118, 0
	v_mov_b32_e32 v119, 0
	v_mov_b32_e32 v120, 0
	v_mov_b32_e32 v121, 0
	v_mov_b32_e32 v122, 0
	v_mov_b32_e32 v123, 0
	v_mov_b32_e32 v124, 0
	v_mov_b32_e32 v125, 0
	v_mov_b32_e32 v126, 0
	v_mov_b32_e32 v127, 0
	v_mov_b32_e32 v128, 0
	v_mov_b32_e32 v129, 0
	v_mov_b32_e32 v130, 0
	v_mov_b32_e32 v131, 0
	v_mov_b32_e32 v132, 0
	v_mov_b32_e32 v133, 0
	v_mov_b32_e32 v134, 0
	v_mov_b32_e32 v135, 0
	v_mov_b32_e32 v136, 0
	v_mov_b32_e32 v137, 0
	v_mov_b32_e32 v138, 0
	v_mov_b32_e32 v139, 0
	v_mov_b32_e32 v140, 0
	v_mov_b32_e32 v141, 0
	v_mov_b32_e32 v142, 0
	v_mov_b32_e32 v143, 0
	v_mov_b32_e32 v144, 0
	v_mov_b32_e32 v145, 0
	v_mov_b32_e32 v146, 0
	v_mov_b32_e32 v147, 0
	s_and_saveexec_b64 s[10:11], vcc
	s_cbranch_execz .LBB0_530
; #define LAS __attribute__((address_space(3)))
; __device__ __forceinline__ float bflo(unsigned w) { return __uint_as_float(w << 16); }
; __device__ __forceinline__ float bfhi(unsigned w) { return __uint_as_float(w & 0xffff0000u); }
; __device__ __forceinline__ f32x4 mfma16(bf16x8 colfrag, bf16x8 rowfrag, f32x4 acc) { return __builtin_amdgcn_mfma_f32_16x16x32_bf16(colfrag, rowfrag, acc, 0, 0, 0); }
; __device__ void s5c_item(const Params& p, int l, int item, LAS unsigned char* lds) {
;     ...
;         u32x2 uwv[16];
;         if (active) {
; #pragma unroll
;             for (int j = 0; j < 16; ++j) uwv[j] = *(const u32x2*)(proj + (size_t)((mt * 16 + fr) * 16 + j) * NPROJ + C_U + g * 16 + 4 * fq);
;         } else {
; #pragma unroll
;             for (int j = 0; j < 16; ++j) uwv[j] = (u32x2){0u, 0u};
;         }
;         __syncthreads();
;         if (active) {
; #pragma unroll
;             for (int j = 0; j < 16; ++j) { f32x4 acc = (f32x4){0.f, 0.f, 0.f, 0.f};
; #pragma unroll
;                 for (int ks = 0; ks < 8; ++ks) if (ks <= (j >> 1)) acc = mfma16(tf[j - 2 * ks], a[ks], acc);
; #pragma unroll
;                 for (int kk = 0; kk < 4; ++kk) { const bf16x8 b = *(const LAS bf16x8*)(lds + (j * 16 + fr) * 272 + (kk * 32 + fq * 8) * 2); acc = mfma16(b, a[8 + kk], acc); }
;                 bf16_t* up = proj + (size_t)((mt * 16 + fr) * 16 + j) * NPROJ + C_U + g * 16 + 4 * fq;
;                 const u32x2 uw = uwv[j];
;                 const float y0 = acc[0] + dsk[0] * bflo(uw.x), y1 = acc[1] + dsk[1] * bfhi(uw.x), y2 = acc[2] + dsk[2] * bflo(uw.y), y3 = acc[3] + dsk[3] * bfhi(uw.y);
	v_mad_i64_i32 v[118:119], s[14:15], v242, s96, v[156:157]
	v_mad_i64_i32 v[120:121], s[14:15], v241, s96, v[156:157]
	v_mad_i64_i32 v[124:125], s[14:15], v239, s96, v[156:157]
	v_mad_i64_i32 v[122:123], s[14:15], v240, s96, v[156:157]
	global_load_dwordx2 v[146:147], v[118:119], off
	global_load_dwordx2 v[144:145], v[120:121], off
	global_load_dwordx2 v[142:143], v[122:123], off
	global_load_dwordx2 v[140:141], v[124:125], off
	v_mad_i64_i32 v[118:119], s[14:15], v227, s96, v[156:157]
	v_mad_i64_i32 v[120:121], s[14:15], v226, s96, v[156:157]
	v_mad_i64_i32 v[124:125], s[14:15], v224, s96, v[156:157]
	v_mad_i64_i32 v[122:123], s[14:15], v225, s96, v[156:157]
	global_load_dwordx2 v[138:139], v[118:119], off
	global_load_dwordx2 v[136:137], v[120:121], off
	global_load_dwordx2 v[134:135], v[122:123], off
	global_load_dwordx2 v[132:133], v[124:125], off
	v_mad_i64_i32 v[118:119], s[14:15], v223, s96, v[156:157]
	v_mad_i64_i32 v[120:121], s[14:15], v222, s96, v[156:157]
	v_mad_i64_i32 v[124:125], s[14:15], v220, s96, v[156:157]
	v_mad_i64_i32 v[122:123], s[14:15], v221, s96, v[156:157]
	global_load_dwordx2 v[130:131], v[118:119], off
	global_load_dwordx2 v[128:129], v[120:121], off
	global_load_dwordx2 v[126:127], v[122:123], off
	s_nop 0
	global_load_dwordx2 v[124:125], v[124:125], off
	v_mad_i64_i32 v[118:119], s[14:15], v219, s96, v[156:157]
	v_mad_i64_i32 v[120:121], s[14:15], v205, s96, v[156:157]
	v_mad_i64_i32 v[206:207], s[14:15], v149, s96, v[156:157]
	v_mad_i64_i32 v[244:245], s[14:15], v148, s96, v[156:157]
	global_load_dwordx2 v[122:123], v[118:119], off
	s_nop 0
	global_load_dwordx2 v[120:121], v[120:121], off
	s_nop 0
	global_load_dwordx2 v[118:119], v[206:207], off
	s_nop 0
	global_load_dwordx2 v[206:207], v[244:245], off
.LBB0_530:
	s_or_b64 exec, exec, s[10:11]
	s_waitcnt lgkmcnt(0)
	s_barrier
	s_and_saveexec_b64 s[10:11], vcc
	s_cbranch_execz .LBB0_525
	ds_read_b128 v[74:77], v78
	ds_read_b128 v[6:9], v78 offset:1024
	ds_read_b128 v[10:13], v78 offset:3072
	ds_read_b128 v[82:85], v78 offset:4096
	ds_read_b128 v[14:17], v78 offset:5120
	ds_read_b128 v[86:89], v78 offset:6144
	ds_read_b128 v[18:21], v78 offset:7168
	ds_read_b128 v[90:93], v78 offset:8192
	ds_read_b128 v[22:25], v78 offset:9216
	ds_read_b128 v[94:97], v78 offset:10240
	ds_read_b128 v[26:29], v78 offset:11264
	ds_read_b128 v[102:105], v78 offset:12288
	ds_read_b128 v[30:33], v78 offset:13312
	ds_read_b128 v[106:109], v78 offset:14336
	ds_read_b128 v[34:37], v78 offset:15360
	ds_read_b128 v[78:81], v78 offset:2048
	s_waitcnt lgkmcnt(0)
	ds_read_b128 v[248:251], v0
	s_waitcnt vmcnt(15)
	v_mfma_f32_16x16x32_bf16 v[244:247], v[74:77], v[42:45], 0
	v_mad_i64_i32 v[242:243], s[14:15], v242, s96, v[156:157]
	s_waitcnt lgkmcnt(0)
	v_mfma_f32_16x16x32_bf16 v[244:247], v[248:251], v[70:73], v[244:247]
	ds_read_b128 v[248:251], v0 offset:64
	s_waitcnt lgkmcnt(0)
	v_mfma_f32_16x16x32_bf16 v[244:247], v[248:251], v[98:101], v[244:247]
	ds_read_b128 v[248:251], v0 offset:128
	s_waitcnt lgkmcnt(0)
	v_mfma_f32_16x16x32_bf16 v[244:247], v[248:251], v[110:113], v[244:247]
	ds_read_b128 v[248:251], v0 offset:192
	s_waitcnt lgkmcnt(0)
	v_mfma_f32_16x16x32_bf16 v[244:247], v[248:251], v[114:117], v[244:247]
	v_lshlrev_b32_e32 v248, 16, v147
	v_and_b32_e32 v249, 0xffff0000, v147
	s_nop 5
	v_pk_fma_f32 v[246:247], v[4:5], v[248:249], v[246:247]
	s_nop 0
	v_mul_f32_e32 v147, 0x3d372713, v246
	v_mul_f32_e32 v147, v246, v147
	v_fma_f32 v147, v246, v147, v246
	v_mul_f32_e32 v147, 0x3f4c422a, v147
	v_add_f32_e32 v147, v147, v147
	v_mul_f32_e32 v147, 0xbfb8aa3b, v147
	v_exp_f32_e32 v147, v147
	s_nop 0
	v_add_f32_e32 v147, 1.0, v147
	v_rcp_f32_e32 v248, v147
	v_mul_f32_e32 v147, 0x3d372713, v247
	v_mul_f32_e32 v147, v247, v147
	v_fma_f32 v147, v247, v147, v247
	v_mul_f32_e32 v147, 0x3f4c422a, v147
	v_add_f32_e32 v147, v147, v147
	v_mul_f32_e32 v147, 0xbfb8aa3b, v147
	v_exp_f32_e32 v147, v147
	s_nop 0
	v_add_f32_e32 v147, 1.0, v147
	v_rcp_f32_e32 v249, v147
	s_nop 0
	v_pk_mul_f32 v[246:247], v[246:247], v[248:249]
	s_nop 0
	v_cvt_pk_bf16_f32 v147, v246, v247
	v_lshlrev_b32_e32 v246, 16, v146
	v_and_b32_e32 v247, 0xffff0000, v146
	v_pk_fma_f32 v[244:245], v[2:3], v[246:247], v[244:245]
	s_nop 0
	v_mul_f32_e32 v146, 0x3d372713, v244
	v_mul_f32_e32 v146, v244, v146
	v_fma_f32 v146, v244, v146, v244
	v_mul_f32_e32 v146, 0x3f4c422a, v146
	v_add_f32_e32 v146, v146, v146
	v_mul_f32_e32 v146, 0xbfb8aa3b, v146
	v_exp_f32_e32 v146, v146
	s_nop 0
	v_add_f32_e32 v146, 1.0, v146
	v_rcp_f32_e32 v246, v146
	v_mul_f32_e32 v146, 0x3d372713, v245
	v_mul_f32_e32 v146, v245, v146
	v_fma_f32 v146, v245, v146, v245
	v_mul_f32_e32 v146, 0x3f4c422a, v146
	v_add_f32_e32 v146, v146, v146
	v_mul_f32_e32 v146, 0xbfb8aa3b, v146
	v_exp_f32_e32 v146, v146
	s_nop 0
	v_add_f32_e32 v146, 1.0, v146
	v_rcp_f32_e32 v247, v146
	s_nop 0
	v_pk_mul_f32 v[244:245], v[244:245], v[246:247]
	s_nop 0
	v_cvt_pk_bf16_f32 v146, v244, v245
	global_store_dwordx2 v[242:243], v[146:147], off
	ds_read_b128 v[246:249], v0 offset:4352
	s_waitcnt vmcnt(15)
	v_mfma_f32_16x16x32_bf16 v[242:245], v[6:9], v[42:45], 0
	v_lshlrev_b32_e32 v146, 16, v145
	v_and_b32_e32 v147, 0xffff0000, v145
	s_waitcnt lgkmcnt(0)
	v_mfma_f32_16x16x32_bf16 v[242:245], v[246:249], v[70:73], v[242:245]
	ds_read_b128 v[246:249], v0 offset:4416
	s_waitcnt lgkmcnt(0)
	v_mfma_f32_16x16x32_bf16 v[242:245], v[246:249], v[98:101], v[242:245]
	ds_read_b128 v[246:249], v0 offset:4480
	s_waitcnt lgkmcnt(0)
	v_mfma_f32_16x16x32_bf16 v[242:245], v[246:249], v[110:113], v[242:245]
	ds_read_b128 v[246:249], v0 offset:4544
	s_waitcnt lgkmcnt(0)
; #define LAS __attribute__((address_space(3)))
; __device__ __forceinline__ float bflo(unsigned w) { return __uint_as_float(w << 16); }
; __device__ __forceinline__ float bfhi(unsigned w) { return __uint_as_float(w & 0xffff0000u); }
; __device__ __forceinline__ unsigned cvt_pk_bf16(float lo, float hi) { const f32x2 f = {lo, hi}; const bf16n2 v = __builtin_convertvector(f, bf16n2); return __builtin_bit_cast(unsigned, v); }
; __device__ __forceinline__ float gelu_tanh(float x) { const float u = 0.7978845608f * (x + 0.044715f * x * x * x); return x * sigmoidf_(2.f * u); }
; __device__ __forceinline__ f32x4 mfma16(bf16x8 colfrag, bf16x8 rowfrag, f32x4 acc) { return __builtin_amdgcn_mfma_f32_16x16x32_bf16(colfrag, rowfrag, acc, 0, 0, 0); }
; __device__ void s5c_item(const Params& p, int l, int item, LAS unsigned char* lds) {
;     ...
;             for (int j = 0; j < 16; ++j) { f32x4 acc = (f32x4){0.f, 0.f, 0.f, 0.f};
; #pragma unroll
;                 for (int ks = 0; ks < 8; ++ks) if (ks <= (j >> 1)) acc = mfma16(tf[j - 2 * ks], a[ks], acc);
; #pragma unroll
;                 for (int kk = 0; kk < 4; ++kk) { const bf16x8 b = *(const LAS bf16x8*)(lds + (j * 16 + fr) * 272 + (kk * 32 + fq * 8) * 2); acc = mfma16(b, a[8 + kk], acc); }
;                 bf16_t* up = proj + (size_t)((mt * 16 + fr) * 16 + j) * NPROJ + C_U + g * 16 + 4 * fq;
;                 const u32x2 uw = uwv[j];
;                 const float y0 = acc[0] + dsk[0] * bflo(uw.x), y1 = acc[1] + dsk[1] * bfhi(uw.x), y2 = acc[2] + dsk[2] * bflo(uw.y), y3 = acc[3] + dsk[3] * bfhi(uw.y);
;                 u32x2 ow; ow.x = cvt_pk_bf16(gelu_tanh(y0), gelu_tanh(y1)); ow.y = cvt_pk_bf16(gelu_tanh(y2), gelu_tanh(y3));
;                 if (!p.dry) *(u32x2*)up = ow;
	v_mfma_f32_16x16x32_bf16 v[242:245], v[246:249], v[114:117], v[242:245]
	s_nop 7
	v_pk_fma_f32 v[146:147], v[4:5], v[146:147], v[244:245]
	s_nop 0
	v_mul_f32_e32 v145, 0x3d372713, v146
	v_mul_f32_e32 v145, v146, v145
	v_fma_f32 v145, v146, v145, v146
	v_mul_f32_e32 v145, 0x3f4c422a, v145
	v_add_f32_e32 v145, v145, v145
	v_mul_f32_e32 v145, 0xbfb8aa3b, v145
	v_exp_f32_e32 v145, v145
	s_nop 0
	v_add_f32_e32 v145, 1.0, v145
	v_rcp_f32_e32 v244, v145
	v_mul_f32_e32 v145, 0x3d372713, v147
	v_mul_f32_e32 v145, v147, v145
	v_fma_f32 v145, v147, v145, v147
	v_mul_f32_e32 v145, 0x3f4c422a, v145
	v_add_f32_e32 v145, v145, v145
	v_mul_f32_e32 v145, 0xbfb8aa3b, v145
	v_exp_f32_e32 v145, v145
	s_nop 0
	v_add_f32_e32 v145, 1.0, v145
	v_rcp_f32_e32 v245, v145
	s_nop 0
	v_pk_mul_f32 v[146:147], v[146:147], v[244:245]
	s_nop 0
	v_cvt_pk_bf16_f32 v145, v146, v147
	v_lshlrev_b32_e32 v146, 16, v144
	v_and_b32_e32 v147, 0xffff0000, v144
	v_pk_fma_f32 v[146:147], v[2:3], v[146:147], v[242:243]
	s_nop 0
	v_mul_f32_e32 v144, 0x3d372713, v146
	v_mul_f32_e32 v144, v146, v144
	v_fma_f32 v144, v146, v144, v146
	v_mul_f32_e32 v144, 0x3f4c422a, v144
	v_add_f32_e32 v144, v144, v144
	v_mul_f32_e32 v144, 0xbfb8aa3b, v144
	v_exp_f32_e32 v144, v144
	s_nop 0
	v_add_f32_e32 v144, 1.0, v144
	v_rcp_f32_e32 v242, v144
	v_mul_f32_e32 v144, 0x3d372713, v147
	v_mul_f32_e32 v144, v147, v144
	v_fma_f32 v144, v147, v144, v147
	v_mul_f32_e32 v144, 0x3f4c422a, v144
	v_add_f32_e32 v144, v144, v144
	v_mul_f32_e32 v144, 0xbfb8aa3b, v144
	v_exp_f32_e32 v144, v144
	s_nop 0
	v_add_f32_e32 v144, 1.0, v144
	v_rcp_f32_e32 v243, v144
	s_nop 0
	v_pk_mul_f32 v[146:147], v[146:147], v[242:243]
	s_nop 0
	v_cvt_pk_bf16_f32 v144, v146, v147
	v_mad_i64_i32 v[146:147], s[14:15], v241, s96, v[156:157]
	global_store_dwordx2 v[146:147], v[144:145], off
	ds_read_b128 v[242:245], v0 offset:8704
	s_waitcnt vmcnt(15)
	v_mfma_f32_16x16x32_bf16 v[144:147], v[78:81], v[42:45], 0
	v_mfma_f32_16x16x32_bf16 v[144:147], v[74:77], v[58:61], v[144:147]
	s_waitcnt lgkmcnt(0)
	v_mfma_f32_16x16x32_bf16 v[144:147], v[242:245], v[70:73], v[144:147]
	ds_read_b128 v[242:245], v0 offset:8768
	s_waitcnt lgkmcnt(0)
	v_mfma_f32_16x16x32_bf16 v[144:147], v[242:245], v[98:101], v[144:147]
	ds_read_b128 v[242:245], v0 offset:8832
	s_waitcnt lgkmcnt(0)
	v_mfma_f32_16x16x32_bf16 v[144:147], v[242:245], v[110:113], v[144:147]
	ds_read_b128 v[242:245], v0 offset:8896
	s_waitcnt lgkmcnt(0)
	v_mfma_f32_16x16x32_bf16 v[144:147], v[242:245], v[114:117], v[144:147]
	v_lshlrev_b32_e32 v242, 16, v143
	v_and_b32_e32 v243, 0xffff0000, v143
	s_nop 5
	v_pk_fma_f32 v[146:147], v[4:5], v[242:243], v[146:147]
	s_nop 0
	v_mul_f32_e32 v143, 0x3d372713, v146
	v_mul_f32_e32 v143, v146, v143
	v_fma_f32 v143, v146, v143, v146
	v_mul_f32_e32 v143, 0x3f4c422a, v143
	v_add_f32_e32 v143, v143, v143
	v_mul_f32_e32 v143, 0xbfb8aa3b, v143
	v_exp_f32_e32 v143, v143
	s_nop 0
	v_add_f32_e32 v143, 1.0, v143
	v_rcp_f32_e32 v242, v143
	v_mul_f32_e32 v143, 0x3d372713, v147
	v_mul_f32_e32 v143, v147, v143
	v_fma_f32 v143, v147, v143, v147
	v_mul_f32_e32 v143, 0x3f4c422a, v143
	v_add_f32_e32 v143, v143, v143
	v_mul_f32_e32 v143, 0xbfb8aa3b, v143
	v_exp_f32_e32 v143, v143
	s_nop 0
	v_add_f32_e32 v143, 1.0, v143
	v_rcp_f32_e32 v243, v143
	s_nop 0
	v_pk_mul_f32 v[146:147], v[146:147], v[242:243]
	s_nop 0
	v_cvt_pk_bf16_f32 v143, v146, v147
	v_lshlrev_b32_e32 v146, 16, v142
	v_and_b32_e32 v147, 0xffff0000, v142
	v_pk_fma_f32 v[144:145], v[2:3], v[146:147], v[144:145]
	s_nop 0
	v_mul_f32_e32 v142, 0x3d372713, v144
	v_mul_f32_e32 v142, v144, v142
	v_fma_f32 v142, v144, v142, v144
	v_mul_f32_e32 v142, 0x3f4c422a, v142
	v_add_f32_e32 v142, v142, v142
	v_mul_f32_e32 v142, 0xbfb8aa3b, v142
	v_exp_f32_e32 v142, v142
	s_nop 0
	v_add_f32_e32 v142, 1.0, v142
	v_rcp_f32_e32 v146, v142
	v_mul_f32_e32 v142, 0x3d372713, v145
	v_mul_f32_e32 v142, v145, v142
	v_fma_f32 v142, v145, v142, v145
	v_mul_f32_e32 v142, 0x3f4c422a, v142
	v_add_f32_e32 v142, v142, v142
	v_mul_f32_e32 v142, 0xbfb8aa3b, v142
	v_exp_f32_e32 v142, v142
	s_nop 0
	v_add_f32_e32 v142, 1.0, v142
	v_rcp_f32_e32 v147, v142
	s_nop 0
	v_pk_mul_f32 v[144:145], v[144:145], v[146:147]
	s_nop 0
	v_cvt_pk_bf16_f32 v142, v144, v145
	v_mad_i64_i32 v[144:145], s[14:15], v240, s96, v[156:157]
	global_store_dwordx2 v[144:145], v[142:143], off
	ds_read_b128 v[240:243], v0 offset:13056
	s_waitcnt vmcnt(15)
	v_mfma_f32_16x16x32_bf16 v[142:145], v[10:13], v[42:45], 0
	v_lshlrev_b32_e32 v146, 16, v141
	v_and_b32_e32 v147, 0xffff0000, v141
	v_mfma_f32_16x16x32_bf16 v[142:145], v[6:9], v[58:61], v[142:145]
	s_waitcnt lgkmcnt(0)
	v_mfma_f32_16x16x32_bf16 v[142:145], v[240:243], v[70:73], v[142:145]
	ds_read_b128 v[240:243], v0 offset:13120
	s_waitcnt lgkmcnt(0)
	v_mfma_f32_16x16x32_bf16 v[142:145], v[240:243], v[98:101], v[142:145]
	ds_read_b128 v[240:243], v0 offset:13184
	s_waitcnt lgkmcnt(0)
	v_mfma_f32_16x16x32_bf16 v[142:145], v[240:243], v[110:113], v[142:145]
	ds_read_b128 v[240:243], v0 offset:13248
	s_waitcnt lgkmcnt(0)
; #define LAS __attribute__((address_space(3)))
; __device__ __forceinline__ float bflo(unsigned w) { return __uint_as_float(w << 16); }
; __device__ __forceinline__ float bfhi(unsigned w) { return __uint_as_float(w & 0xffff0000u); }
; __device__ __forceinline__ unsigned cvt_pk_bf16(float lo, float hi) { const f32x2 f = {lo, hi}; const bf16n2 v = __builtin_convertvector(f, bf16n2); return __builtin_bit_cast(unsigned, v); }
; __device__ __forceinline__ float gelu_tanh(float x) { const float u = 0.7978845608f * (x + 0.044715f * x * x * x); return x * sigmoidf_(2.f * u); }
; __device__ __forceinline__ f32x4 mfma16(bf16x8 colfrag, bf16x8 rowfrag, f32x4 acc) { return __builtin_amdgcn_mfma_f32_16x16x32_bf16(colfrag, rowfrag, acc, 0, 0, 0); }
; __device__ __forceinline__ float sigmoidf_(float x) { return __builtin_amdgcn_rcpf(1.0f + __expf(-x)); }
; __device__ __forceinline__ float siluf_(float x) { return x * sigmoidf_(x); }
; __device__ __forceinline__ float logsigmoidf_(float x) { return fminf(x, 0.f) - __logf(1.0f + __expf(-fabsf(x))); }
; __device__ void s5c_item(const Params& p, int l, int item, LAS unsigned char* lds) {
;     ...
;             for (int j = 0; j < 16; ++j) { f32x4 acc = (f32x4){0.f, 0.f, 0.f, 0.f};
; #pragma unroll
;                 for (int ks = 0; ks < 8; ++ks) if (ks <= (j >> 1)) acc = mfma16(tf[j - 2 * ks], a[ks], acc);
; #pragma unroll
;                 for (int kk = 0; kk < 4; ++kk) { const bf16x8 b = *(const LAS bf16x8*)(lds + (j * 16 + fr) * 272 + (kk * 32 + fq * 8) * 2); acc = mfma16(b, a[8 + kk], acc); }
;                 bf16_t* up = proj + (size_t)((mt * 16 + fr) * 16 + j) * NPROJ + C_U + g * 16 + 4 * fq;
;                 const u32x2 uw = uwv[j];
;                 const float y0 = acc[0] + dsk[0] * bflo(uw.x), y1 = acc[1] + dsk[1] * bfhi(uw.x), y2 = acc[2] + dsk[2] * bflo(uw.y), y3 = acc[3] + dsk[3] * bfhi(uw.y);
;                 u32x2 ow; ow.x = cvt_pk_bf16(gelu_tanh(y0), gelu_tanh(y1)); ow.y = cvt_pk_bf16(gelu_tanh(y2), gelu_tanh(y3));
;                 if (!p.dry) *(u32x2*)up = ow;
;                 __builtin_amdgcn_sched_barrier(0); }
	v_mfma_f32_16x16x32_bf16 v[142:145], v[240:243], v[114:117], v[142:145]
	s_nop 7
	v_pk_fma_f32 v[144:145], v[4:5], v[146:147], v[144:145]
	s_nop 0
	v_mul_f32_e32 v141, 0x3d372713, v144
	v_mul_f32_e32 v141, v144, v141
	v_fma_f32 v141, v144, v141, v144
	v_mul_f32_e32 v141, 0x3f4c422a, v141
	v_add_f32_e32 v141, v141, v141
	v_mul_f32_e32 v141, 0xbfb8aa3b, v141
	v_exp_f32_e32 v141, v141
	s_nop 0
	v_add_f32_e32 v141, 1.0, v141
	v_rcp_f32_e32 v146, v141
	v_mul_f32_e32 v141, 0x3d372713, v145
	v_mul_f32_e32 v141, v145, v141
	v_fma_f32 v141, v145, v141, v145
	v_mul_f32_e32 v141, 0x3f4c422a, v141
	v_add_f32_e32 v141, v141, v141
	v_mul_f32_e32 v141, 0xbfb8aa3b, v141
	v_exp_f32_e32 v141, v141
	s_nop 0
	v_add_f32_e32 v141, 1.0, v141
	v_rcp_f32_e32 v147, v141
	s_nop 0
	v_pk_mul_f32 v[144:145], v[144:145], v[146:147]
	s_nop 0
	v_cvt_pk_bf16_f32 v141, v144, v145
	v_lshlrev_b32_e32 v144, 16, v140
	v_and_b32_e32 v145, 0xffff0000, v140
	v_pk_fma_f32 v[142:143], v[2:3], v[144:145], v[142:143]
	s_nop 0
	v_mul_f32_e32 v140, 0x3d372713, v142
	v_mul_f32_e32 v140, v142, v140
	v_fma_f32 v140, v142, v140, v142
	v_mul_f32_e32 v140, 0x3f4c422a, v140
	v_add_f32_e32 v140, v140, v140
	v_mul_f32_e32 v140, 0xbfb8aa3b, v140
	v_exp_f32_e32 v140, v140
	s_nop 0
	v_add_f32_e32 v140, 1.0, v140
	v_rcp_f32_e32 v144, v140
	v_mul_f32_e32 v140, 0x3d372713, v143
	v_mul_f32_e32 v140, v143, v140
	v_fma_f32 v140, v143, v140, v143
	v_mul_f32_e32 v140, 0x3f4c422a, v140
	v_add_f32_e32 v140, v140, v140
	v_mul_f32_e32 v140, 0xbfb8aa3b, v140
	v_exp_f32_e32 v140, v140
	s_nop 0
	v_add_f32_e32 v140, 1.0, v140
	v_rcp_f32_e32 v145, v140
	s_nop 0
	v_pk_mul_f32 v[142:143], v[142:143], v[144:145]
	s_nop 0
	v_cvt_pk_bf16_f32 v140, v142, v143
	v_mad_i64_i32 v[142:143], s[14:15], v239, s96, v[156:157]
	global_store_dwordx2 v[142:143], v[140:141], off
	s_waitcnt vmcnt(15)
	v_mfma_f32_16x16x32_bf16 v[140:143], v[82:85], v[42:45], 0
	ds_read_b128 v[144:147], v0 offset:17408
	v_mfma_f32_16x16x32_bf16 v[140:143], v[78:81], v[58:61], v[140:143]
	v_mfma_f32_16x16x32_bf16 v[140:143], v[74:77], v[46:49], v[140:143]
	s_waitcnt lgkmcnt(0)
	v_mfma_f32_16x16x32_bf16 v[140:143], v[144:147], v[70:73], v[140:143]
	ds_read_b128 v[144:147], v0 offset:17472
	s_waitcnt lgkmcnt(0)
	v_mfma_f32_16x16x32_bf16 v[140:143], v[144:147], v[98:101], v[140:143]
	ds_read_b128 v[144:147], v0 offset:17536
	s_waitcnt lgkmcnt(0)
	v_mfma_f32_16x16x32_bf16 v[140:143], v[144:147], v[110:113], v[140:143]
	ds_read_b128 v[144:147], v0 offset:17600
	s_waitcnt lgkmcnt(0)
	v_mfma_f32_16x16x32_bf16 v[140:143], v[144:147], v[114:117], v[140:143]
	v_lshlrev_b32_e32 v144, 16, v139
	v_and_b32_e32 v145, 0xffff0000, v139
	s_nop 5
	v_pk_fma_f32 v[142:143], v[4:5], v[144:145], v[142:143]
	s_nop 0
	v_mul_f32_e32 v139, 0x3d372713, v142
	v_mul_f32_e32 v139, v142, v139
	v_fma_f32 v139, v142, v139, v142
	v_mul_f32_e32 v139, 0x3f4c422a, v139
	v_add_f32_e32 v139, v139, v139
	v_mul_f32_e32 v139, 0xbfb8aa3b, v139
	v_exp_f32_e32 v139, v139
	s_nop 0
	v_add_f32_e32 v139, 1.0, v139
	v_rcp_f32_e32 v144, v139
	v_mul_f32_e32 v139, 0x3d372713, v143
	v_mul_f32_e32 v139, v143, v139
	v_fma_f32 v139, v143, v139, v143
	v_mul_f32_e32 v139, 0x3f4c422a, v139
	v_add_f32_e32 v139, v139, v139
	v_mul_f32_e32 v139, 0xbfb8aa3b, v139
	v_exp_f32_e32 v139, v139
	s_nop 0
	v_add_f32_e32 v139, 1.0, v139
	v_rcp_f32_e32 v145, v139
	s_nop 0
	v_pk_mul_f32 v[142:143], v[142:143], v[144:145]
	s_nop 0
	v_cvt_pk_bf16_f32 v139, v142, v143
	v_lshlrev_b32_e32 v142, 16, v138
	v_and_b32_e32 v143, 0xffff0000, v138
	v_pk_fma_f32 v[140:141], v[2:3], v[142:143], v[140:141]
	s_nop 0
	v_mul_f32_e32 v138, 0x3d372713, v140
	v_mul_f32_e32 v138, v140, v138
	v_fma_f32 v138, v140, v138, v140
	v_mul_f32_e32 v138, 0x3f4c422a, v138
	v_add_f32_e32 v138, v138, v138
	v_mul_f32_e32 v138, 0xbfb8aa3b, v138
	v_exp_f32_e32 v138, v138
	s_nop 0
	v_add_f32_e32 v138, 1.0, v138
	v_rcp_f32_e32 v142, v138
	v_mul_f32_e32 v138, 0x3d372713, v141
	v_mul_f32_e32 v138, v141, v138
	v_fma_f32 v138, v141, v138, v141
	v_mul_f32_e32 v138, 0x3f4c422a, v138
	v_add_f32_e32 v138, v138, v138
	v_mul_f32_e32 v138, 0xbfb8aa3b, v138
	v_exp_f32_e32 v138, v138
	s_nop 0
	v_add_f32_e32 v138, 1.0, v138
	v_rcp_f32_e32 v143, v138
	s_nop 0
	v_pk_mul_f32 v[140:141], v[140:141], v[142:143]
	s_nop 0
	v_cvt_pk_bf16_f32 v138, v140, v141
	v_mad_i64_i32 v[140:141], s[14:15], v227, s96, v[156:157]
	global_store_dwordx2 v[140:141], v[138:139], off
	s_waitcnt vmcnt(15)
	v_mfma_f32_16x16x32_bf16 v[138:141], v[14:17], v[42:45], 0
	ds_read_b128 v[142:145], v0 offset:21760
	v_mfma_f32_16x16x32_bf16 v[138:141], v[10:13], v[58:61], v[138:141]
	v_mfma_f32_16x16x32_bf16 v[138:141], v[6:9], v[46:49], v[138:141]
	s_waitcnt lgkmcnt(0)
	v_mfma_f32_16x16x32_bf16 v[138:141], v[142:145], v[70:73], v[138:141]
	ds_read_b128 v[142:145], v0 offset:21824
	s_waitcnt lgkmcnt(0)
	v_mfma_f32_16x16x32_bf16 v[138:141], v[142:145], v[98:101], v[138:141]
	ds_read_b128 v[142:145], v0 offset:21888
	s_waitcnt lgkmcnt(0)
	v_mfma_f32_16x16x32_bf16 v[138:141], v[142:145], v[110:113], v[138:141]
	ds_read_b128 v[142:145], v0 offset:21952
	s_waitcnt lgkmcnt(0)
; #define LAS __attribute__((address_space(3)))
; __device__ __forceinline__ float bflo(unsigned w) { return __uint_as_float(w << 16); }
; __device__ __forceinline__ float bfhi(unsigned w) { return __uint_as_float(w & 0xffff0000u); }
; __device__ __forceinline__ unsigned cvt_pk_bf16(float lo, float hi) { const f32x2 f = {lo, hi}; const bf16n2 v = __builtin_convertvector(f, bf16n2); return __builtin_bit_cast(unsigned, v); }
; __device__ __forceinline__ float gelu_tanh(float x) { const float u = 0.7978845608f * (x + 0.044715f * x * x * x); return x * sigmoidf_(2.f * u); }
; __device__ __forceinline__ f32x4 mfma16(bf16x8 colfrag, bf16x8 rowfrag, f32x4 acc) { return __builtin_amdgcn_mfma_f32_16x16x32_bf16(colfrag, rowfrag, acc, 0, 0, 0); }
; __device__ __forceinline__ float sigmoidf_(float x) { return __builtin_amdgcn_rcpf(1.0f + __expf(-x)); }
; __device__ __forceinline__ float siluf_(float x) { return x * sigmoidf_(x); }
; __device__ __forceinline__ float logsigmoidf_(float x) { return fminf(x, 0.f) - __logf(1.0f + __expf(-fabsf(x))); }
; __device__ void s5c_item(const Params& p, int l, int item, LAS unsigned char* lds) {
;     ...
;             for (int j = 0; j < 16; ++j) { f32x4 acc = (f32x4){0.f, 0.f, 0.f, 0.f};
; #pragma unroll
;                 for (int ks = 0; ks < 8; ++ks) if (ks <= (j >> 1)) acc = mfma16(tf[j - 2 * ks], a[ks], acc);
; #pragma unroll
;                 for (int kk = 0; kk < 4; ++kk) { const bf16x8 b = *(const LAS bf16x8*)(lds + (j * 16 + fr) * 272 + (kk * 32 + fq * 8) * 2); acc = mfma16(b, a[8 + kk], acc); }
;                 bf16_t* up = proj + (size_t)((mt * 16 + fr) * 16 + j) * NPROJ + C_U + g * 16 + 4 * fq;
;                 const u32x2 uw = uwv[j];
;                 const float y0 = acc[0] + dsk[0] * bflo(uw.x), y1 = acc[1] + dsk[1] * bfhi(uw.x), y2 = acc[2] + dsk[2] * bflo(uw.y), y3 = acc[3] + dsk[3] * bfhi(uw.y);
;                 u32x2 ow; ow.x = cvt_pk_bf16(gelu_tanh(y0), gelu_tanh(y1)); ow.y = cvt_pk_bf16(gelu_tanh(y2), gelu_tanh(y3));
;                 if (!p.dry) *(u32x2*)up = ow;
;                 __builtin_amdgcn_sched_barrier(0); }
	v_mfma_f32_16x16x32_bf16 v[138:141], v[142:145], v[114:117], v[138:141]
	v_lshlrev_b32_e32 v142, 16, v137
	v_and_b32_e32 v143, 0xffff0000, v137
	s_nop 5
	v_pk_fma_f32 v[140:141], v[4:5], v[142:143], v[140:141]
	s_nop 0
	v_mul_f32_e32 v137, 0x3d372713, v140
	v_mul_f32_e32 v137, v140, v137
	v_fma_f32 v137, v140, v137, v140
	v_mul_f32_e32 v137, 0x3f4c422a, v137
	v_add_f32_e32 v137, v137, v137
	v_mul_f32_e32 v137, 0xbfb8aa3b, v137
	v_exp_f32_e32 v137, v137
	s_nop 0
	v_add_f32_e32 v137, 1.0, v137
	v_rcp_f32_e32 v142, v137
	v_mul_f32_e32 v137, 0x3d372713, v141
	v_mul_f32_e32 v137, v141, v137
	v_fma_f32 v137, v141, v137, v141
	v_mul_f32_e32 v137, 0x3f4c422a, v137
	v_add_f32_e32 v137, v137, v137
	v_mul_f32_e32 v137, 0xbfb8aa3b, v137
	v_exp_f32_e32 v137, v137
	s_nop 0
	v_add_f32_e32 v137, 1.0, v137
	v_rcp_f32_e32 v143, v137
	s_nop 0
	v_pk_mul_f32 v[140:141], v[140:141], v[142:143]
	s_nop 0
	v_cvt_pk_bf16_f32 v137, v140, v141
	v_lshlrev_b32_e32 v140, 16, v136
	v_and_b32_e32 v141, 0xffff0000, v136
	v_pk_fma_f32 v[138:139], v[2:3], v[140:141], v[138:139]
	s_nop 0
	v_mul_f32_e32 v136, 0x3d372713, v138
	v_mul_f32_e32 v136, v138, v136
	v_fma_f32 v136, v138, v136, v138
	v_mul_f32_e32 v136, 0x3f4c422a, v136
	v_add_f32_e32 v136, v136, v136
	v_mul_f32_e32 v136, 0xbfb8aa3b, v136
	v_exp_f32_e32 v136, v136
	s_nop 0
	v_add_f32_e32 v136, 1.0, v136
	v_rcp_f32_e32 v140, v136
	v_mul_f32_e32 v136, 0x3d372713, v139
	v_mul_f32_e32 v136, v139, v136
	v_fma_f32 v136, v139, v136, v139
	v_mul_f32_e32 v136, 0x3f4c422a, v136
	v_add_f32_e32 v136, v136, v136
	v_mul_f32_e32 v136, 0xbfb8aa3b, v136
	v_exp_f32_e32 v136, v136
	s_nop 0
	v_add_f32_e32 v136, 1.0, v136
	v_rcp_f32_e32 v141, v136
	s_nop 0
	v_pk_mul_f32 v[138:139], v[138:139], v[140:141]
	s_nop 0
	v_cvt_pk_bf16_f32 v136, v138, v139
	v_mad_i64_i32 v[138:139], s[14:15], v226, s96, v[156:157]
	global_store_dwordx2 v[138:139], v[136:137], off
	s_waitcnt vmcnt(15)
	v_mfma_f32_16x16x32_bf16 v[136:139], v[86:89], v[42:45], 0
	ds_read_b128 v[140:143], v0 offset:26112
	v_mfma_f32_16x16x32_bf16 v[136:139], v[82:85], v[58:61], v[136:139]
	v_mfma_f32_16x16x32_bf16 v[136:139], v[78:81], v[46:49], v[136:139]
	v_mfma_f32_16x16x32_bf16 v[136:139], v[74:77], v[66:69], v[136:139]
	s_waitcnt lgkmcnt(0)
	v_mfma_f32_16x16x32_bf16 v[136:139], v[140:143], v[70:73], v[136:139]
	ds_read_b128 v[140:143], v0 offset:26176
	s_waitcnt lgkmcnt(0)
	v_mfma_f32_16x16x32_bf16 v[136:139], v[140:143], v[98:101], v[136:139]
	ds_read_b128 v[140:143], v0 offset:26240
	s_waitcnt lgkmcnt(0)
	v_mfma_f32_16x16x32_bf16 v[136:139], v[140:143], v[110:113], v[136:139]
	ds_read_b128 v[140:143], v0 offset:26304
	s_waitcnt lgkmcnt(0)
	v_mfma_f32_16x16x32_bf16 v[136:139], v[140:143], v[114:117], v[136:139]
	v_lshlrev_b32_e32 v140, 16, v135
	v_and_b32_e32 v141, 0xffff0000, v135
	s_nop 5
	v_pk_fma_f32 v[138:139], v[4:5], v[140:141], v[138:139]
	s_nop 0
	v_mul_f32_e32 v135, 0x3d372713, v138
	v_mul_f32_e32 v135, v138, v135
	v_fma_f32 v135, v138, v135, v138
	v_mul_f32_e32 v135, 0x3f4c422a, v135
	v_add_f32_e32 v135, v135, v135
	v_mul_f32_e32 v135, 0xbfb8aa3b, v135
	v_exp_f32_e32 v135, v135
	s_nop 0
	v_add_f32_e32 v135, 1.0, v135
	v_rcp_f32_e32 v140, v135
	v_mul_f32_e32 v135, 0x3d372713, v139
	v_mul_f32_e32 v135, v139, v135
	v_fma_f32 v135, v139, v135, v139
	v_mul_f32_e32 v135, 0x3f4c422a, v135
	v_add_f32_e32 v135, v135, v135
	v_mul_f32_e32 v135, 0xbfb8aa3b, v135
	v_exp_f32_e32 v135, v135
	s_nop 0
	v_add_f32_e32 v135, 1.0, v135
	v_rcp_f32_e32 v141, v135
	s_nop 0
	v_pk_mul_f32 v[138:139], v[138:139], v[140:141]
	s_nop 0
	v_cvt_pk_bf16_f32 v135, v138, v139
	v_lshlrev_b32_e32 v138, 16, v134
	v_and_b32_e32 v139, 0xffff0000, v134
	v_pk_fma_f32 v[136:137], v[2:3], v[138:139], v[136:137]
	s_nop 0
	v_mul_f32_e32 v134, 0x3d372713, v136
	v_mul_f32_e32 v134, v136, v134
	v_fma_f32 v134, v136, v134, v136
	v_mul_f32_e32 v134, 0x3f4c422a, v134
	v_add_f32_e32 v134, v134, v134
	v_mul_f32_e32 v134, 0xbfb8aa3b, v134
	v_exp_f32_e32 v134, v134
	s_nop 0
	v_add_f32_e32 v134, 1.0, v134
	v_rcp_f32_e32 v138, v134
	v_mul_f32_e32 v134, 0x3d372713, v137
	v_mul_f32_e32 v134, v137, v134
	v_fma_f32 v134, v137, v134, v137
	v_mul_f32_e32 v134, 0x3f4c422a, v134
	v_add_f32_e32 v134, v134, v134
	v_mul_f32_e32 v134, 0xbfb8aa3b, v134
	v_exp_f32_e32 v134, v134
	s_nop 0
	v_add_f32_e32 v134, 1.0, v134
	v_rcp_f32_e32 v139, v134
	s_nop 0
	v_pk_mul_f32 v[136:137], v[136:137], v[138:139]
	s_nop 0
	v_cvt_pk_bf16_f32 v134, v136, v137
	v_mad_i64_i32 v[136:137], s[14:15], v225, s96, v[156:157]
	global_store_dwordx2 v[136:137], v[134:135], off
	s_waitcnt vmcnt(15)
	v_mfma_f32_16x16x32_bf16 v[134:137], v[18:21], v[42:45], 0
	ds_read_b128 v[138:141], v0 offset:30464
	v_mfma_f32_16x16x32_bf16 v[134:137], v[14:17], v[58:61], v[134:137]
	v_mfma_f32_16x16x32_bf16 v[134:137], v[10:13], v[46:49], v[134:137]
	v_mfma_f32_16x16x32_bf16 v[134:137], v[6:9], v[66:69], v[134:137]
	s_waitcnt lgkmcnt(0)
	v_mfma_f32_16x16x32_bf16 v[134:137], v[138:141], v[70:73], v[134:137]
	ds_read_b128 v[138:141], v0 offset:30528
	s_waitcnt lgkmcnt(0)
	v_mfma_f32_16x16x32_bf16 v[134:137], v[138:141], v[98:101], v[134:137]
	ds_read_b128 v[138:141], v0 offset:30592
	s_waitcnt lgkmcnt(0)
	v_mfma_f32_16x16x32_bf16 v[134:137], v[138:141], v[110:113], v[134:137]
	ds_read_b128 v[138:141], v0 offset:30656
	s_waitcnt lgkmcnt(0)
; #define LAS __attribute__((address_space(3)))
; __device__ __forceinline__ float bflo(unsigned w) { return __uint_as_float(w << 16); }
; __device__ __forceinline__ float bfhi(unsigned w) { return __uint_as_float(w & 0xffff0000u); }
; __device__ __forceinline__ unsigned cvt_pk_bf16(float lo, float hi) { const f32x2 f = {lo, hi}; const bf16n2 v = __builtin_convertvector(f, bf16n2); return __builtin_bit_cast(unsigned, v); }
; __device__ __forceinline__ float gelu_tanh(float x) { const float u = 0.7978845608f * (x + 0.044715f * x * x * x); return x * sigmoidf_(2.f * u); }
; __device__ __forceinline__ f32x4 mfma16(bf16x8 colfrag, bf16x8 rowfrag, f32x4 acc) { return __builtin_amdgcn_mfma_f32_16x16x32_bf16(colfrag, rowfrag, acc, 0, 0, 0); }
; __device__ __forceinline__ float sigmoidf_(float x) { return __builtin_amdgcn_rcpf(1.0f + __expf(-x)); }
; __device__ __forceinline__ float siluf_(float x) { return x * sigmoidf_(x); }
; __device__ __forceinline__ float logsigmoidf_(float x) { return fminf(x, 0.f) - __logf(1.0f + __expf(-fabsf(x))); }
; __device__ void s5c_item(const Params& p, int l, int item, LAS unsigned char* lds) {
;     ...
;             for (int j = 0; j < 16; ++j) { f32x4 acc = (f32x4){0.f, 0.f, 0.f, 0.f};
; #pragma unroll
;                 for (int ks = 0; ks < 8; ++ks) if (ks <= (j >> 1)) acc = mfma16(tf[j - 2 * ks], a[ks], acc);
; #pragma unroll
;                 for (int kk = 0; kk < 4; ++kk) { const bf16x8 b = *(const LAS bf16x8*)(lds + (j * 16 + fr) * 272 + (kk * 32 + fq * 8) * 2); acc = mfma16(b, a[8 + kk], acc); }
;                 bf16_t* up = proj + (size_t)((mt * 16 + fr) * 16 + j) * NPROJ + C_U + g * 16 + 4 * fq;
;                 const u32x2 uw = uwv[j];
;                 const float y0 = acc[0] + dsk[0] * bflo(uw.x), y1 = acc[1] + dsk[1] * bfhi(uw.x), y2 = acc[2] + dsk[2] * bflo(uw.y), y3 = acc[3] + dsk[3] * bfhi(uw.y);
;                 u32x2 ow; ow.x = cvt_pk_bf16(gelu_tanh(y0), gelu_tanh(y1)); ow.y = cvt_pk_bf16(gelu_tanh(y2), gelu_tanh(y3));
;                 if (!p.dry) *(u32x2*)up = ow;
;                 __builtin_amdgcn_sched_barrier(0); }
	v_mfma_f32_16x16x32_bf16 v[134:137], v[138:141], v[114:117], v[134:137]
	v_lshlrev_b32_e32 v138, 16, v133
	v_and_b32_e32 v139, 0xffff0000, v133
	s_nop 5
	v_pk_fma_f32 v[136:137], v[4:5], v[138:139], v[136:137]
	s_nop 0
	v_mul_f32_e32 v133, 0x3d372713, v136
	v_mul_f32_e32 v133, v136, v133
	v_fma_f32 v133, v136, v133, v136
	v_mul_f32_e32 v133, 0x3f4c422a, v133
	v_add_f32_e32 v133, v133, v133
	v_mul_f32_e32 v133, 0xbfb8aa3b, v133
	v_exp_f32_e32 v133, v133
	s_nop 0
	v_add_f32_e32 v133, 1.0, v133
	v_rcp_f32_e32 v138, v133
	v_mul_f32_e32 v133, 0x3d372713, v137
	v_mul_f32_e32 v133, v137, v133
	v_fma_f32 v133, v137, v133, v137
	v_mul_f32_e32 v133, 0x3f4c422a, v133
	v_add_f32_e32 v133, v133, v133
	v_mul_f32_e32 v133, 0xbfb8aa3b, v133
	v_exp_f32_e32 v133, v133
	s_nop 0
	v_add_f32_e32 v133, 1.0, v133
	v_rcp_f32_e32 v139, v133
	s_nop 0
	v_pk_mul_f32 v[136:137], v[136:137], v[138:139]
	s_nop 0
	v_cvt_pk_bf16_f32 v133, v136, v137
	v_lshlrev_b32_e32 v136, 16, v132
	v_and_b32_e32 v137, 0xffff0000, v132
	v_pk_fma_f32 v[134:135], v[2:3], v[136:137], v[134:135]
	s_nop 0
	v_mul_f32_e32 v132, 0x3d372713, v134
	v_mul_f32_e32 v132, v134, v132
	v_fma_f32 v132, v134, v132, v134
	v_mul_f32_e32 v132, 0x3f4c422a, v132
	v_add_f32_e32 v132, v132, v132
	v_mul_f32_e32 v132, 0xbfb8aa3b, v132
	v_exp_f32_e32 v132, v132
	s_nop 0
	v_add_f32_e32 v132, 1.0, v132
	v_rcp_f32_e32 v136, v132
	v_mul_f32_e32 v132, 0x3d372713, v135
	v_mul_f32_e32 v132, v135, v132
	v_fma_f32 v132, v135, v132, v135
	v_mul_f32_e32 v132, 0x3f4c422a, v132
	v_add_f32_e32 v132, v132, v132
	v_mul_f32_e32 v132, 0xbfb8aa3b, v132
	v_exp_f32_e32 v132, v132
	s_nop 0
	v_add_f32_e32 v132, 1.0, v132
	v_rcp_f32_e32 v137, v132
	s_nop 0
	v_pk_mul_f32 v[134:135], v[134:135], v[136:137]
	s_nop 0
	v_cvt_pk_bf16_f32 v132, v134, v135
	v_mad_i64_i32 v[134:135], s[14:15], v224, s96, v[156:157]
	global_store_dwordx2 v[134:135], v[132:133], off
	s_waitcnt vmcnt(15)
	v_mfma_f32_16x16x32_bf16 v[132:135], v[90:93], v[42:45], 0
	ds_read_b128 v[136:139], v0 offset:34816
	v_mfma_f32_16x16x32_bf16 v[132:135], v[86:89], v[58:61], v[132:135]
	v_mfma_f32_16x16x32_bf16 v[132:135], v[82:85], v[46:49], v[132:135]
	v_mfma_f32_16x16x32_bf16 v[132:135], v[78:81], v[66:69], v[132:135]
	v_mfma_f32_16x16x32_bf16 v[132:135], v[74:77], v[54:57], v[132:135]
	s_waitcnt lgkmcnt(0)
	v_mfma_f32_16x16x32_bf16 v[132:135], v[136:139], v[70:73], v[132:135]
	ds_read_b128 v[136:139], v0 offset:34880
	s_waitcnt lgkmcnt(0)
	v_mfma_f32_16x16x32_bf16 v[132:135], v[136:139], v[98:101], v[132:135]
	ds_read_b128 v[136:139], v0 offset:34944
	s_waitcnt lgkmcnt(0)
	v_mfma_f32_16x16x32_bf16 v[132:135], v[136:139], v[110:113], v[132:135]
	ds_read_b128 v[136:139], v0 offset:35008
	s_waitcnt lgkmcnt(0)
	v_mfma_f32_16x16x32_bf16 v[132:135], v[136:139], v[114:117], v[132:135]
	v_lshlrev_b32_e32 v136, 16, v131
	v_and_b32_e32 v137, 0xffff0000, v131
	s_nop 5
	v_pk_fma_f32 v[134:135], v[4:5], v[136:137], v[134:135]
	s_nop 0
	v_mul_f32_e32 v131, 0x3d372713, v134
	v_mul_f32_e32 v131, v134, v131
	v_fma_f32 v131, v134, v131, v134
	v_mul_f32_e32 v131, 0x3f4c422a, v131
	v_add_f32_e32 v131, v131, v131
	v_mul_f32_e32 v131, 0xbfb8aa3b, v131
	v_exp_f32_e32 v131, v131
	s_nop 0
	v_add_f32_e32 v131, 1.0, v131
	v_rcp_f32_e32 v136, v131
	v_mul_f32_e32 v131, 0x3d372713, v135
	v_mul_f32_e32 v131, v135, v131
	v_fma_f32 v131, v135, v131, v135
	v_mul_f32_e32 v131, 0x3f4c422a, v131
	v_add_f32_e32 v131, v131, v131
	v_mul_f32_e32 v131, 0xbfb8aa3b, v131
	v_exp_f32_e32 v131, v131
	s_nop 0
	v_add_f32_e32 v131, 1.0, v131
	v_rcp_f32_e32 v137, v131
	s_nop 0
	v_pk_mul_f32 v[134:135], v[134:135], v[136:137]
	s_nop 0
	v_cvt_pk_bf16_f32 v131, v134, v135
	v_lshlrev_b32_e32 v134, 16, v130
	v_and_b32_e32 v135, 0xffff0000, v130
	v_pk_fma_f32 v[132:133], v[2:3], v[134:135], v[132:133]
	s_nop 0
	v_mul_f32_e32 v130, 0x3d372713, v132
	v_mul_f32_e32 v130, v132, v130
	v_fma_f32 v130, v132, v130, v132
	v_mul_f32_e32 v130, 0x3f4c422a, v130
	v_add_f32_e32 v130, v130, v130
	v_mul_f32_e32 v130, 0xbfb8aa3b, v130
	v_exp_f32_e32 v130, v130
	s_nop 0
	v_add_f32_e32 v130, 1.0, v130
	v_rcp_f32_e32 v134, v130
	v_mul_f32_e32 v130, 0x3d372713, v133
	v_mul_f32_e32 v130, v133, v130
	v_fma_f32 v130, v133, v130, v133
	v_mul_f32_e32 v130, 0x3f4c422a, v130
	v_add_f32_e32 v130, v130, v130
	v_mul_f32_e32 v130, 0xbfb8aa3b, v130
	v_exp_f32_e32 v130, v130
	s_nop 0
	v_add_f32_e32 v130, 1.0, v130
	v_rcp_f32_e32 v135, v130
	s_nop 0
	v_pk_mul_f32 v[132:133], v[132:133], v[134:135]
	s_nop 0
	v_cvt_pk_bf16_f32 v130, v132, v133
	v_mad_i64_i32 v[132:133], s[14:15], v223, s96, v[156:157]
	global_store_dwordx2 v[132:133], v[130:131], off
	s_waitcnt vmcnt(15)
	v_mfma_f32_16x16x32_bf16 v[130:133], v[22:25], v[42:45], 0
	ds_read_b128 v[134:137], v0 offset:39168
	v_mfma_f32_16x16x32_bf16 v[130:133], v[18:21], v[58:61], v[130:133]
	v_mfma_f32_16x16x32_bf16 v[130:133], v[14:17], v[46:49], v[130:133]
	v_mfma_f32_16x16x32_bf16 v[130:133], v[10:13], v[66:69], v[130:133]
	v_mfma_f32_16x16x32_bf16 v[130:133], v[6:9], v[54:57], v[130:133]
	s_waitcnt lgkmcnt(0)
	v_mfma_f32_16x16x32_bf16 v[130:133], v[134:137], v[70:73], v[130:133]
	ds_read_b128 v[134:137], v0 offset:39232
	s_waitcnt lgkmcnt(0)
	v_mfma_f32_16x16x32_bf16 v[130:133], v[134:137], v[98:101], v[130:133]
	ds_read_b128 v[134:137], v0 offset:39296
	s_waitcnt lgkmcnt(0)
	v_mfma_f32_16x16x32_bf16 v[130:133], v[134:137], v[110:113], v[130:133]
	ds_read_b128 v[134:137], v0 offset:39360
	s_waitcnt lgkmcnt(0)
; #define LAS __attribute__((address_space(3)))
; __device__ __forceinline__ float bflo(unsigned w) { return __uint_as_float(w << 16); }
; __device__ __forceinline__ float bfhi(unsigned w) { return __uint_as_float(w & 0xffff0000u); }
; __device__ __forceinline__ unsigned cvt_pk_bf16(float lo, float hi) { const f32x2 f = {lo, hi}; const bf16n2 v = __builtin_convertvector(f, bf16n2); return __builtin_bit_cast(unsigned, v); }
; __device__ __forceinline__ float gelu_tanh(float x) { const float u = 0.7978845608f * (x + 0.044715f * x * x * x); return x * sigmoidf_(2.f * u); }
; __device__ __forceinline__ f32x4 mfma16(bf16x8 colfrag, bf16x8 rowfrag, f32x4 acc) { return __builtin_amdgcn_mfma_f32_16x16x32_bf16(colfrag, rowfrag, acc, 0, 0, 0); }
; __device__ __forceinline__ float sigmoidf_(float x) { return __builtin_amdgcn_rcpf(1.0f + __expf(-x)); }
; __device__ __forceinline__ float siluf_(float x) { return x * sigmoidf_(x); }
; __device__ __forceinline__ float logsigmoidf_(float x) { return fminf(x, 0.f) - __logf(1.0f + __expf(-fabsf(x))); }
; __device__ void s5c_item(const Params& p, int l, int item, LAS unsigned char* lds) {
;     ...
;             for (int j = 0; j < 16; ++j) { f32x4 acc = (f32x4){0.f, 0.f, 0.f, 0.f};
; #pragma unroll
;                 for (int ks = 0; ks < 8; ++ks) if (ks <= (j >> 1)) acc = mfma16(tf[j - 2 * ks], a[ks], acc);
; #pragma unroll
;                 for (int kk = 0; kk < 4; ++kk) { const bf16x8 b = *(const LAS bf16x8*)(lds + (j * 16 + fr) * 272 + (kk * 32 + fq * 8) * 2); acc = mfma16(b, a[8 + kk], acc); }
;                 bf16_t* up = proj + (size_t)((mt * 16 + fr) * 16 + j) * NPROJ + C_U + g * 16 + 4 * fq;
;                 const u32x2 uw = uwv[j];
;                 const float y0 = acc[0] + dsk[0] * bflo(uw.x), y1 = acc[1] + dsk[1] * bfhi(uw.x), y2 = acc[2] + dsk[2] * bflo(uw.y), y3 = acc[3] + dsk[3] * bfhi(uw.y);
;                 u32x2 ow; ow.x = cvt_pk_bf16(gelu_tanh(y0), gelu_tanh(y1)); ow.y = cvt_pk_bf16(gelu_tanh(y2), gelu_tanh(y3));
;                 if (!p.dry) *(u32x2*)up = ow;
;                 __builtin_amdgcn_sched_barrier(0); }
	v_mfma_f32_16x16x32_bf16 v[130:133], v[134:137], v[114:117], v[130:133]
	v_lshlrev_b32_e32 v134, 16, v129
	v_and_b32_e32 v135, 0xffff0000, v129
	s_nop 5
	v_pk_fma_f32 v[132:133], v[4:5], v[134:135], v[132:133]
	s_nop 0
	v_mul_f32_e32 v129, 0x3d372713, v132
	v_mul_f32_e32 v129, v132, v129
	v_fma_f32 v129, v132, v129, v132
	v_mul_f32_e32 v129, 0x3f4c422a, v129
	v_add_f32_e32 v129, v129, v129
	v_mul_f32_e32 v129, 0xbfb8aa3b, v129
	v_exp_f32_e32 v129, v129
	s_nop 0
	v_add_f32_e32 v129, 1.0, v129
	v_rcp_f32_e32 v134, v129
	v_mul_f32_e32 v129, 0x3d372713, v133
	v_mul_f32_e32 v129, v133, v129
	v_fma_f32 v129, v133, v129, v133
	v_mul_f32_e32 v129, 0x3f4c422a, v129
	v_add_f32_e32 v129, v129, v129
	v_mul_f32_e32 v129, 0xbfb8aa3b, v129
	v_exp_f32_e32 v129, v129
	s_nop 0
	v_add_f32_e32 v129, 1.0, v129
	v_rcp_f32_e32 v135, v129
	s_nop 0
	v_pk_mul_f32 v[132:133], v[132:133], v[134:135]
	s_nop 0
	v_cvt_pk_bf16_f32 v129, v132, v133
	v_lshlrev_b32_e32 v132, 16, v128
	v_and_b32_e32 v133, 0xffff0000, v128
	v_pk_fma_f32 v[130:131], v[2:3], v[132:133], v[130:131]
	s_nop 0
	v_mul_f32_e32 v128, 0x3d372713, v130
	v_mul_f32_e32 v128, v130, v128
	v_fma_f32 v128, v130, v128, v130
	v_mul_f32_e32 v128, 0x3f4c422a, v128
	v_add_f32_e32 v128, v128, v128
	v_mul_f32_e32 v128, 0xbfb8aa3b, v128
	v_exp_f32_e32 v128, v128
	s_nop 0
	v_add_f32_e32 v128, 1.0, v128
	v_rcp_f32_e32 v132, v128
	v_mul_f32_e32 v128, 0x3d372713, v131
	v_mul_f32_e32 v128, v131, v128
	v_fma_f32 v128, v131, v128, v131
	v_mul_f32_e32 v128, 0x3f4c422a, v128
	v_add_f32_e32 v128, v128, v128
	v_mul_f32_e32 v128, 0xbfb8aa3b, v128
	v_exp_f32_e32 v128, v128
	s_nop 0
	v_add_f32_e32 v128, 1.0, v128
	v_rcp_f32_e32 v133, v128
	s_nop 0
	v_pk_mul_f32 v[130:131], v[130:131], v[132:133]
	s_nop 0
	v_cvt_pk_bf16_f32 v128, v130, v131
	v_mad_i64_i32 v[130:131], s[14:15], v222, s96, v[156:157]
	global_store_dwordx2 v[130:131], v[128:129], off
	s_waitcnt vmcnt(15)
	v_mfma_f32_16x16x32_bf16 v[128:131], v[94:97], v[42:45], 0
	ds_read_b128 v[132:135], v0 offset:43520
	v_mfma_f32_16x16x32_bf16 v[128:131], v[90:93], v[58:61], v[128:131]
	v_mfma_f32_16x16x32_bf16 v[128:131], v[86:89], v[46:49], v[128:131]
	v_mfma_f32_16x16x32_bf16 v[128:131], v[82:85], v[66:69], v[128:131]
	v_mfma_f32_16x16x32_bf16 v[128:131], v[78:81], v[54:57], v[128:131]
	v_mfma_f32_16x16x32_bf16 v[128:131], v[74:77], v[62:65], v[128:131]
	s_waitcnt lgkmcnt(0)
	v_mfma_f32_16x16x32_bf16 v[128:131], v[132:135], v[70:73], v[128:131]
	ds_read_b128 v[132:135], v0 offset:43584
	s_waitcnt lgkmcnt(0)
	v_mfma_f32_16x16x32_bf16 v[128:131], v[132:135], v[98:101], v[128:131]
	ds_read_b128 v[132:135], v0 offset:43648
	s_waitcnt lgkmcnt(0)
	v_mfma_f32_16x16x32_bf16 v[128:131], v[132:135], v[110:113], v[128:131]
	ds_read_b128 v[132:135], v0 offset:43712
	s_waitcnt lgkmcnt(0)
	v_mfma_f32_16x16x32_bf16 v[128:131], v[132:135], v[114:117], v[128:131]
	v_lshlrev_b32_e32 v132, 16, v127
	v_and_b32_e32 v133, 0xffff0000, v127
	s_nop 5
	v_pk_fma_f32 v[130:131], v[4:5], v[132:133], v[130:131]
	s_nop 0
	v_mul_f32_e32 v127, 0x3d372713, v130
	v_mul_f32_e32 v127, v130, v127
	v_fma_f32 v127, v130, v127, v130
	v_mul_f32_e32 v127, 0x3f4c422a, v127
	v_add_f32_e32 v127, v127, v127
	v_mul_f32_e32 v127, 0xbfb8aa3b, v127
	v_exp_f32_e32 v127, v127
	s_nop 0
	v_add_f32_e32 v127, 1.0, v127
	v_rcp_f32_e32 v132, v127
	v_mul_f32_e32 v127, 0x3d372713, v131
	v_mul_f32_e32 v127, v131, v127
	v_fma_f32 v127, v131, v127, v131
	v_mul_f32_e32 v127, 0x3f4c422a, v127
	v_add_f32_e32 v127, v127, v127
	v_mul_f32_e32 v127, 0xbfb8aa3b, v127
	v_exp_f32_e32 v127, v127
	s_nop 0
	v_add_f32_e32 v127, 1.0, v127
	v_rcp_f32_e32 v133, v127
	s_nop 0
	v_pk_mul_f32 v[130:131], v[130:131], v[132:133]
	s_nop 0
	v_cvt_pk_bf16_f32 v127, v130, v131
	v_lshlrev_b32_e32 v130, 16, v126
	v_and_b32_e32 v131, 0xffff0000, v126
	v_pk_fma_f32 v[128:129], v[2:3], v[130:131], v[128:129]
	s_nop 0
	v_mul_f32_e32 v126, 0x3d372713, v128
	v_mul_f32_e32 v126, v128, v126
	v_fma_f32 v126, v128, v126, v128
	v_mul_f32_e32 v126, 0x3f4c422a, v126
	v_add_f32_e32 v126, v126, v126
	v_mul_f32_e32 v126, 0xbfb8aa3b, v126
	v_exp_f32_e32 v126, v126
	s_nop 0
	v_add_f32_e32 v126, 1.0, v126
	v_rcp_f32_e32 v130, v126
	v_mul_f32_e32 v126, 0x3d372713, v129
	v_mul_f32_e32 v126, v129, v126
	v_fma_f32 v126, v129, v126, v129
	v_mul_f32_e32 v126, 0x3f4c422a, v126
	v_add_f32_e32 v126, v126, v126
	v_mul_f32_e32 v126, 0xbfb8aa3b, v126
	v_exp_f32_e32 v126, v126
	s_nop 0
	v_add_f32_e32 v126, 1.0, v126
	v_rcp_f32_e32 v131, v126
	s_nop 0
	v_pk_mul_f32 v[128:129], v[128:129], v[130:131]
	s_nop 0
	v_cvt_pk_bf16_f32 v126, v128, v129
	v_mad_i64_i32 v[128:129], s[14:15], v221, s96, v[156:157]
	global_store_dwordx2 v[128:129], v[126:127], off
	s_waitcnt vmcnt(15)
	v_mfma_f32_16x16x32_bf16 v[126:129], v[26:29], v[42:45], 0
	ds_read_b128 v[130:133], v0 offset:47872
	v_mfma_f32_16x16x32_bf16 v[126:129], v[22:25], v[58:61], v[126:129]
	v_mfma_f32_16x16x32_bf16 v[126:129], v[18:21], v[46:49], v[126:129]
	v_mfma_f32_16x16x32_bf16 v[126:129], v[14:17], v[66:69], v[126:129]
	v_mfma_f32_16x16x32_bf16 v[126:129], v[10:13], v[54:57], v[126:129]
	v_mfma_f32_16x16x32_bf16 v[126:129], v[6:9], v[62:65], v[126:129]
	s_waitcnt lgkmcnt(0)
	v_mfma_f32_16x16x32_bf16 v[126:129], v[130:133], v[70:73], v[126:129]
	ds_read_b128 v[130:133], v0 offset:47936
	s_waitcnt lgkmcnt(0)
	v_mfma_f32_16x16x32_bf16 v[126:129], v[130:133], v[98:101], v[126:129]
	ds_read_b128 v[130:133], v0 offset:48000
	s_waitcnt lgkmcnt(0)
	v_mfma_f32_16x16x32_bf16 v[126:129], v[130:133], v[110:113], v[126:129]
	ds_read_b128 v[130:133], v0 offset:48064
	s_waitcnt lgkmcnt(0)
; #define LAS __attribute__((address_space(3)))
; __device__ __forceinline__ float bflo(unsigned w) { return __uint_as_float(w << 16); }
; __device__ __forceinline__ float bfhi(unsigned w) { return __uint_as_float(w & 0xffff0000u); }
; __device__ __forceinline__ unsigned cvt_pk_bf16(float lo, float hi) { const f32x2 f = {lo, hi}; const bf16n2 v = __builtin_convertvector(f, bf16n2); return __builtin_bit_cast(unsigned, v); }
; __device__ __forceinline__ float gelu_tanh(float x) { const float u = 0.7978845608f * (x + 0.044715f * x * x * x); return x * sigmoidf_(2.f * u); }
; __device__ __forceinline__ f32x4 mfma16(bf16x8 colfrag, bf16x8 rowfrag, f32x4 acc) { return __builtin_amdgcn_mfma_f32_16x16x32_bf16(colfrag, rowfrag, acc, 0, 0, 0); }
; __device__ __forceinline__ float sigmoidf_(float x) { return __builtin_amdgcn_rcpf(1.0f + __expf(-x)); }
; __device__ __forceinline__ float siluf_(float x) { return x * sigmoidf_(x); }
; __device__ __forceinline__ float logsigmoidf_(float x) { return fminf(x, 0.f) - __logf(1.0f + __expf(-fabsf(x))); }
; __device__ void s5c_item(const Params& p, int l, int item, LAS unsigned char* lds) {
;     ...
;             for (int j = 0; j < 16; ++j) { f32x4 acc = (f32x4){0.f, 0.f, 0.f, 0.f};
; #pragma unroll
;                 for (int ks = 0; ks < 8; ++ks) if (ks <= (j >> 1)) acc = mfma16(tf[j - 2 * ks], a[ks], acc);
; #pragma unroll
;                 for (int kk = 0; kk < 4; ++kk) { const bf16x8 b = *(const LAS bf16x8*)(lds + (j * 16 + fr) * 272 + (kk * 32 + fq * 8) * 2); acc = mfma16(b, a[8 + kk], acc); }
;                 bf16_t* up = proj + (size_t)((mt * 16 + fr) * 16 + j) * NPROJ + C_U + g * 16 + 4 * fq;
;                 const u32x2 uw = uwv[j];
;                 const float y0 = acc[0] + dsk[0] * bflo(uw.x), y1 = acc[1] + dsk[1] * bfhi(uw.x), y2 = acc[2] + dsk[2] * bflo(uw.y), y3 = acc[3] + dsk[3] * bfhi(uw.y);
;                 u32x2 ow; ow.x = cvt_pk_bf16(gelu_tanh(y0), gelu_tanh(y1)); ow.y = cvt_pk_bf16(gelu_tanh(y2), gelu_tanh(y3));
;                 if (!p.dry) *(u32x2*)up = ow;
;                 __builtin_amdgcn_sched_barrier(0); }
	v_mfma_f32_16x16x32_bf16 v[126:129], v[130:133], v[114:117], v[126:129]
	v_lshlrev_b32_e32 v130, 16, v125
	v_and_b32_e32 v131, 0xffff0000, v125
	s_nop 5
	v_pk_fma_f32 v[128:129], v[4:5], v[130:131], v[128:129]
	s_nop 0
	v_mul_f32_e32 v125, 0x3d372713, v128
	v_mul_f32_e32 v125, v128, v125
	v_fma_f32 v125, v128, v125, v128
	v_mul_f32_e32 v125, 0x3f4c422a, v125
	v_add_f32_e32 v125, v125, v125
	v_mul_f32_e32 v125, 0xbfb8aa3b, v125
	v_exp_f32_e32 v125, v125
	s_nop 0
	v_add_f32_e32 v125, 1.0, v125
	v_rcp_f32_e32 v130, v125
	v_mul_f32_e32 v125, 0x3d372713, v129
	v_mul_f32_e32 v125, v129, v125
	v_fma_f32 v125, v129, v125, v129
	v_mul_f32_e32 v125, 0x3f4c422a, v125
	v_add_f32_e32 v125, v125, v125
	v_mul_f32_e32 v125, 0xbfb8aa3b, v125
	v_exp_f32_e32 v125, v125
	s_nop 0
	v_add_f32_e32 v125, 1.0, v125
	v_rcp_f32_e32 v131, v125
	s_nop 0
	v_pk_mul_f32 v[128:129], v[128:129], v[130:131]
	s_nop 0
	v_cvt_pk_bf16_f32 v125, v128, v129
	v_lshlrev_b32_e32 v128, 16, v124
	v_and_b32_e32 v129, 0xffff0000, v124
	v_pk_fma_f32 v[126:127], v[2:3], v[128:129], v[126:127]
	s_nop 0
	v_mul_f32_e32 v124, 0x3d372713, v126
	v_mul_f32_e32 v124, v126, v124
	v_fma_f32 v124, v126, v124, v126
	v_mul_f32_e32 v124, 0x3f4c422a, v124
	v_add_f32_e32 v124, v124, v124
	v_mul_f32_e32 v124, 0xbfb8aa3b, v124
	v_exp_f32_e32 v124, v124
	s_nop 0
	v_add_f32_e32 v124, 1.0, v124
	v_rcp_f32_e32 v128, v124
	v_mul_f32_e32 v124, 0x3d372713, v127
	v_mul_f32_e32 v124, v127, v124
	v_fma_f32 v124, v127, v124, v127
	v_mul_f32_e32 v124, 0x3f4c422a, v124
	v_add_f32_e32 v124, v124, v124
	v_mul_f32_e32 v124, 0xbfb8aa3b, v124
	v_exp_f32_e32 v124, v124
	s_nop 0
	v_add_f32_e32 v124, 1.0, v124
	v_rcp_f32_e32 v129, v124
	s_nop 0
	v_pk_mul_f32 v[126:127], v[126:127], v[128:129]
	s_nop 0
	v_cvt_pk_bf16_f32 v124, v126, v127
	v_mad_i64_i32 v[126:127], s[14:15], v220, s96, v[156:157]
	global_store_dwordx2 v[126:127], v[124:125], off
	s_waitcnt vmcnt(15)
	v_mfma_f32_16x16x32_bf16 v[124:127], v[102:105], v[42:45], 0
	ds_read_b128 v[128:131], v0 offset:52224
	v_mfma_f32_16x16x32_bf16 v[124:127], v[94:97], v[58:61], v[124:127]
	v_mfma_f32_16x16x32_bf16 v[124:127], v[90:93], v[46:49], v[124:127]
	v_mfma_f32_16x16x32_bf16 v[124:127], v[86:89], v[66:69], v[124:127]
	v_mfma_f32_16x16x32_bf16 v[124:127], v[82:85], v[54:57], v[124:127]
	v_mfma_f32_16x16x32_bf16 v[124:127], v[78:81], v[62:65], v[124:127]
	v_mfma_f32_16x16x32_bf16 v[124:127], v[74:77], v[50:53], v[124:127]
	s_waitcnt lgkmcnt(0)
	v_mfma_f32_16x16x32_bf16 v[124:127], v[128:131], v[70:73], v[124:127]
	ds_read_b128 v[128:131], v0 offset:52288
	s_waitcnt lgkmcnt(0)
	v_mfma_f32_16x16x32_bf16 v[124:127], v[128:131], v[98:101], v[124:127]
	ds_read_b128 v[128:131], v0 offset:52352
	s_waitcnt lgkmcnt(0)
	v_mfma_f32_16x16x32_bf16 v[124:127], v[128:131], v[110:113], v[124:127]
	ds_read_b128 v[128:131], v0 offset:52416
	s_waitcnt lgkmcnt(0)
	v_mfma_f32_16x16x32_bf16 v[124:127], v[128:131], v[114:117], v[124:127]
	v_lshlrev_b32_e32 v128, 16, v123
	v_and_b32_e32 v129, 0xffff0000, v123
	s_nop 5
	v_pk_fma_f32 v[126:127], v[4:5], v[128:129], v[126:127]
	s_nop 0
	v_mul_f32_e32 v123, 0x3d372713, v126
	v_mul_f32_e32 v123, v126, v123
	v_fma_f32 v123, v126, v123, v126
	v_mul_f32_e32 v123, 0x3f4c422a, v123
	v_add_f32_e32 v123, v123, v123
	v_mul_f32_e32 v123, 0xbfb8aa3b, v123
	v_exp_f32_e32 v123, v123
	s_nop 0
	v_add_f32_e32 v123, 1.0, v123
	v_rcp_f32_e32 v128, v123
	v_mul_f32_e32 v123, 0x3d372713, v127
	v_mul_f32_e32 v123, v127, v123
	v_fma_f32 v123, v127, v123, v127
	v_mul_f32_e32 v123, 0x3f4c422a, v123
	v_add_f32_e32 v123, v123, v123
	v_mul_f32_e32 v123, 0xbfb8aa3b, v123
	v_exp_f32_e32 v123, v123
	s_nop 0
	v_add_f32_e32 v123, 1.0, v123
	v_rcp_f32_e32 v129, v123
	s_nop 0
	v_pk_mul_f32 v[126:127], v[126:127], v[128:129]
	s_nop 0
	v_cvt_pk_bf16_f32 v123, v126, v127
	v_lshlrev_b32_e32 v126, 16, v122
	v_and_b32_e32 v127, 0xffff0000, v122
	v_pk_fma_f32 v[124:125], v[2:3], v[126:127], v[124:125]
	s_nop 0
	v_mul_f32_e32 v122, 0x3d372713, v124
	v_mul_f32_e32 v122, v124, v122
	v_fma_f32 v122, v124, v122, v124
	v_mul_f32_e32 v122, 0x3f4c422a, v122
	v_add_f32_e32 v122, v122, v122
	v_mul_f32_e32 v122, 0xbfb8aa3b, v122
	v_exp_f32_e32 v122, v122
	s_nop 0
	v_add_f32_e32 v122, 1.0, v122
	v_rcp_f32_e32 v126, v122
	v_mul_f32_e32 v122, 0x3d372713, v125
	v_mul_f32_e32 v122, v125, v122
	v_fma_f32 v122, v125, v122, v125
	v_mul_f32_e32 v122, 0x3f4c422a, v122
	v_add_f32_e32 v122, v122, v122
	v_mul_f32_e32 v122, 0xbfb8aa3b, v122
	v_exp_f32_e32 v122, v122
	s_nop 0
	v_add_f32_e32 v122, 1.0, v122
	v_rcp_f32_e32 v127, v122
	s_nop 0
	v_pk_mul_f32 v[124:125], v[124:125], v[126:127]
	s_nop 0
	v_cvt_pk_bf16_f32 v122, v124, v125
	v_mad_i64_i32 v[124:125], s[14:15], v219, s96, v[156:157]
	global_store_dwordx2 v[124:125], v[122:123], off
	s_waitcnt vmcnt(15)
	v_mfma_f32_16x16x32_bf16 v[122:125], v[30:33], v[42:45], 0
	ds_read_b128 v[126:129], v0 offset:56576
	v_mfma_f32_16x16x32_bf16 v[122:125], v[26:29], v[58:61], v[122:125]
	v_mfma_f32_16x16x32_bf16 v[122:125], v[22:25], v[46:49], v[122:125]
	v_mfma_f32_16x16x32_bf16 v[122:125], v[18:21], v[66:69], v[122:125]
	v_mfma_f32_16x16x32_bf16 v[122:125], v[14:17], v[54:57], v[122:125]
	v_mfma_f32_16x16x32_bf16 v[122:125], v[10:13], v[62:65], v[122:125]
	v_mfma_f32_16x16x32_bf16 v[122:125], v[6:9], v[50:53], v[122:125]
	s_waitcnt lgkmcnt(0)
	v_mfma_f32_16x16x32_bf16 v[122:125], v[126:129], v[70:73], v[122:125]
	ds_read_b128 v[126:129], v0 offset:56640
	s_waitcnt lgkmcnt(0)
	v_mfma_f32_16x16x32_bf16 v[122:125], v[126:129], v[98:101], v[122:125]
	ds_read_b128 v[126:129], v0 offset:56704
	s_waitcnt lgkmcnt(0)
; #define LAS __attribute__((address_space(3)))
; __device__ __forceinline__ float bflo(unsigned w) { return __uint_as_float(w << 16); }
; __device__ __forceinline__ float bfhi(unsigned w) { return __uint_as_float(w & 0xffff0000u); }
; __device__ __forceinline__ unsigned cvt_pk_bf16(float lo, float hi) { const f32x2 f = {lo, hi}; const bf16n2 v = __builtin_convertvector(f, bf16n2); return __builtin_bit_cast(unsigned, v); }
; __device__ __forceinline__ float gelu_tanh(float x) { const float u = 0.7978845608f * (x + 0.044715f * x * x * x); return x * sigmoidf_(2.f * u); }
; __device__ __forceinline__ f32x4 mfma16(bf16x8 colfrag, bf16x8 rowfrag, f32x4 acc) { return __builtin_amdgcn_mfma_f32_16x16x32_bf16(colfrag, rowfrag, acc, 0, 0, 0); }
; __device__ void s5c_item(const Params& p, int l, int item, LAS unsigned char* lds) {
;     ...
;             for (int j = 0; j < 16; ++j) { f32x4 acc = (f32x4){0.f, 0.f, 0.f, 0.f};
; #pragma unroll
;                 for (int ks = 0; ks < 8; ++ks) if (ks <= (j >> 1)) acc = mfma16(tf[j - 2 * ks], a[ks], acc);
; #pragma unroll
;                 for (int kk = 0; kk < 4; ++kk) { const bf16x8 b = *(const LAS bf16x8*)(lds + (j * 16 + fr) * 272 + (kk * 32 + fq * 8) * 2); acc = mfma16(b, a[8 + kk], acc); }
;                 bf16_t* up = proj + (size_t)((mt * 16 + fr) * 16 + j) * NPROJ + C_U + g * 16 + 4 * fq;
;                 const u32x2 uw = uwv[j];
;                 const float y0 = acc[0] + dsk[0] * bflo(uw.x), y1 = acc[1] + dsk[1] * bfhi(uw.x), y2 = acc[2] + dsk[2] * bflo(uw.y), y3 = acc[3] + dsk[3] * bfhi(uw.y);
;                 u32x2 ow; ow.x = cvt_pk_bf16(gelu_tanh(y0), gelu_tanh(y1)); ow.y = cvt_pk_bf16(gelu_tanh(y2), gelu_tanh(y3));
;                 if (!p.dry) *(u32x2*)up = ow;
;                 __builtin_amdgcn_sched_barrier(0); }
	v_mfma_f32_16x16x32_bf16 v[122:125], v[126:129], v[110:113], v[122:125]
	ds_read_b128 v[126:129], v0 offset:56768
	s_waitcnt lgkmcnt(0)
	v_mfma_f32_16x16x32_bf16 v[122:125], v[126:129], v[114:117], v[122:125]
	v_lshlrev_b32_e32 v126, 16, v121
	v_and_b32_e32 v127, 0xffff0000, v121
	s_nop 5
	v_pk_fma_f32 v[124:125], v[4:5], v[126:127], v[124:125]
	s_nop 0
	v_mul_f32_e32 v121, 0x3d372713, v124
	v_mul_f32_e32 v121, v124, v121
	v_fma_f32 v121, v124, v121, v124
	v_mul_f32_e32 v121, 0x3f4c422a, v121
	v_add_f32_e32 v121, v121, v121
	v_mul_f32_e32 v121, 0xbfb8aa3b, v121
	v_exp_f32_e32 v121, v121
	s_nop 0
	v_add_f32_e32 v121, 1.0, v121
	v_rcp_f32_e32 v126, v121
	v_mul_f32_e32 v121, 0x3d372713, v125
	v_mul_f32_e32 v121, v125, v121
	v_fma_f32 v121, v125, v121, v125
	v_mul_f32_e32 v121, 0x3f4c422a, v121
	v_add_f32_e32 v121, v121, v121
	v_mul_f32_e32 v121, 0xbfb8aa3b, v121
	v_exp_f32_e32 v121, v121
	s_nop 0
	v_add_f32_e32 v121, 1.0, v121
	v_rcp_f32_e32 v127, v121
	s_nop 0
	v_pk_mul_f32 v[124:125], v[124:125], v[126:127]
	s_nop 0
	v_cvt_pk_bf16_f32 v121, v124, v125
	v_lshlrev_b32_e32 v124, 16, v120
	v_and_b32_e32 v125, 0xffff0000, v120
	v_pk_fma_f32 v[122:123], v[2:3], v[124:125], v[122:123]
	s_nop 0
	v_mul_f32_e32 v120, 0x3d372713, v122
	v_mul_f32_e32 v120, v122, v120
	v_fma_f32 v120, v122, v120, v122
	v_mul_f32_e32 v120, 0x3f4c422a, v120
	v_add_f32_e32 v120, v120, v120
	v_mul_f32_e32 v120, 0xbfb8aa3b, v120
	v_exp_f32_e32 v120, v120
	s_nop 0
	v_add_f32_e32 v120, 1.0, v120
	v_rcp_f32_e32 v124, v120
	v_mul_f32_e32 v120, 0x3d372713, v123
	v_mul_f32_e32 v120, v123, v120
	v_fma_f32 v120, v123, v120, v123
	v_mul_f32_e32 v120, 0x3f4c422a, v120
	v_add_f32_e32 v120, v120, v120
	v_mul_f32_e32 v120, 0xbfb8aa3b, v120
	v_exp_f32_e32 v120, v120
	s_nop 0
	v_add_f32_e32 v120, 1.0, v120
	v_rcp_f32_e32 v125, v120
	s_nop 0
	v_pk_mul_f32 v[122:123], v[122:123], v[124:125]
	s_nop 0
	v_cvt_pk_bf16_f32 v120, v122, v123
	v_mad_i64_i32 v[122:123], s[14:15], v205, s96, v[156:157]
	global_store_dwordx2 v[122:123], v[120:121], off
	s_waitcnt vmcnt(15)
	v_mfma_f32_16x16x32_bf16 v[106:109], v[106:109], v[42:45], 0
	v_mfma_f32_16x16x32_bf16 v[102:105], v[102:105], v[58:61], v[106:109]
	v_mfma_f32_16x16x32_bf16 v[94:97], v[94:97], v[46:49], v[102:105]
	v_mfma_f32_16x16x32_bf16 v[90:93], v[90:93], v[66:69], v[94:97]
	v_mfma_f32_16x16x32_bf16 v[86:89], v[86:89], v[54:57], v[90:93]
	v_mfma_f32_16x16x32_bf16 v[82:85], v[82:85], v[62:65], v[86:89]
	v_mfma_f32_16x16x32_bf16 v[78:81], v[78:81], v[50:53], v[82:85]
	s_nop 5
	v_lshlrev_b32_e32 v86, 16, v119
	v_and_b32_e32 v87, 0xffff0000, v119
	ds_read_b128 v[82:85], v0 offset:60928
	v_mfma_f32_16x16x32_bf16 v[74:77], v[74:77], v[38:41], v[78:81]
	s_nop 2
	ds_read_b128 v[78:81], v0 offset:60992
	s_waitcnt lgkmcnt(1)
	v_mfma_f32_16x16x32_bf16 v[74:77], v[82:85], v[70:73], v[74:77]
	ds_read_b128 v[82:85], v0 offset:61056
	s_waitcnt lgkmcnt(1)
	v_mfma_f32_16x16x32_bf16 v[74:77], v[78:81], v[98:101], v[74:77]
	ds_read_b128 v[78:81], v0 offset:61120
	s_waitcnt lgkmcnt(1)
	v_mfma_f32_16x16x32_bf16 v[74:77], v[82:85], v[110:113], v[74:77]
	v_lshlrev_b32_e32 v82, 16, v118
	v_and_b32_e32 v83, 0xffff0000, v118
	s_waitcnt lgkmcnt(0)
; #define LAS __attribute__((address_space(3)))
; __device__ __forceinline__ float bflo(unsigned w) { return __uint_as_float(w << 16); }
; __device__ __forceinline__ float bfhi(unsigned w) { return __uint_as_float(w & 0xffff0000u); }
; __device__ __forceinline__ unsigned cvt_pk_bf16(float lo, float hi) { const f32x2 f = {lo, hi}; const bf16n2 v = __builtin_convertvector(f, bf16n2); return __builtin_bit_cast(unsigned, v); }
; __device__ __forceinline__ float gelu_tanh(float x) { const float u = 0.7978845608f * (x + 0.044715f * x * x * x); return x * sigmoidf_(2.f * u); }
; __device__ __forceinline__ f32x4 mfma16(bf16x8 colfrag, bf16x8 rowfrag, f32x4 acc) { return __builtin_amdgcn_mfma_f32_16x16x32_bf16(colfrag, rowfrag, acc, 0, 0, 0); }
; __device__ __forceinline__ float sigmoidf_(float x) { return __builtin_amdgcn_rcpf(1.0f + __expf(-x)); }
; __device__ __forceinline__ float siluf_(float x) { return x * sigmoidf_(x); }
; __device__ __forceinline__ float logsigmoidf_(float x) { return fminf(x, 0.f) - __logf(1.0f + __expf(-fabsf(x))); }
; __device__ void s5c_item(const Params& p, int l, int item, LAS unsigned char* lds) {
;     ...
;             for (int j = 0; j < 16; ++j) { f32x4 acc = (f32x4){0.f, 0.f, 0.f, 0.f};
; #pragma unroll
;                 for (int ks = 0; ks < 8; ++ks) if (ks <= (j >> 1)) acc = mfma16(tf[j - 2 * ks], a[ks], acc);
; #pragma unroll
;                 for (int kk = 0; kk < 4; ++kk) { const bf16x8 b = *(const LAS bf16x8*)(lds + (j * 16 + fr) * 272 + (kk * 32 + fq * 8) * 2); acc = mfma16(b, a[8 + kk], acc); }
;                 bf16_t* up = proj + (size_t)((mt * 16 + fr) * 16 + j) * NPROJ + C_U + g * 16 + 4 * fq;
;                 const u32x2 uw = uwv[j];
;                 const float y0 = acc[0] + dsk[0] * bflo(uw.x), y1 = acc[1] + dsk[1] * bfhi(uw.x), y2 = acc[2] + dsk[2] * bflo(uw.y), y3 = acc[3] + dsk[3] * bfhi(uw.y);
;                 u32x2 ow; ow.x = cvt_pk_bf16(gelu_tanh(y0), gelu_tanh(y1)); ow.y = cvt_pk_bf16(gelu_tanh(y2), gelu_tanh(y3));
;                 if (!p.dry) *(u32x2*)up = ow;
;                 __builtin_amdgcn_sched_barrier(0); }
	v_mfma_f32_16x16x32_bf16 v[74:77], v[78:81], v[114:117], v[74:77]
	s_nop 7
	v_pk_fma_f32 v[76:77], v[4:5], v[86:87], v[76:77]
	v_pk_fma_f32 v[74:75], v[2:3], v[82:83], v[74:75]
	v_mul_f32_e32 v78, 0x3d372713, v76
	v_mul_f32_e32 v79, 0x3d372713, v77
	v_mul_f32_e32 v80, 0x3d372713, v74
	v_mul_f32_e32 v81, 0x3d372713, v75
	v_mul_f32_e32 v78, v76, v78
	v_mul_f32_e32 v79, v77, v79
	v_mul_f32_e32 v80, v74, v80
	v_mul_f32_e32 v81, v75, v81
	v_fma_f32 v78, v76, v78, v76
	v_fma_f32 v79, v77, v79, v77
	v_fma_f32 v80, v74, v80, v74
	v_fma_f32 v81, v75, v81, v75
	v_mul_f32_e32 v78, 0x3f4c422a, v78
	v_mul_f32_e32 v79, 0x3f4c422a, v79
	v_mul_f32_e32 v80, 0x3f4c422a, v80
	v_mul_f32_e32 v81, 0x3f4c422a, v81
	v_add_f32_e32 v78, v78, v78
	v_add_f32_e32 v79, v79, v79
	v_add_f32_e32 v80, v80, v80
	v_add_f32_e32 v81, v81, v81
	v_mul_f32_e32 v78, 0xbfb8aa3b, v78
	v_mul_f32_e32 v79, 0xbfb8aa3b, v79
	v_mul_f32_e32 v80, 0xbfb8aa3b, v80
	v_mul_f32_e32 v81, 0xbfb8aa3b, v81
	v_exp_f32_e32 v78, v78
	v_exp_f32_e32 v79, v79
	v_exp_f32_e32 v80, v80
	v_exp_f32_e32 v81, v81
	v_add_f32_e32 v78, 1.0, v78
	v_add_f32_e32 v79, 1.0, v79
	v_add_f32_e32 v80, 1.0, v80
	v_add_f32_e32 v81, 1.0, v81
	v_rcp_f32_e32 v78, v78
	v_rcp_f32_e32 v79, v79
	v_rcp_f32_e32 v80, v80
	v_rcp_f32_e32 v81, v81
	v_pk_mul_f32 v[76:77], v[76:77], v[78:79]
	s_nop 0
	v_cvt_pk_bf16_f32 v77, v76, v77
	v_pk_mul_f32 v[74:75], v[74:75], v[80:81]
	s_nop 0
	v_cvt_pk_bf16_f32 v76, v74, v75
	v_mad_i64_i32 v[74:75], s[14:15], v149, s96, v[156:157]
	global_store_dwordx2 v[74:75], v[76:77], off
	s_waitcnt vmcnt(15)
	v_mfma_f32_16x16x32_bf16 v[34:37], v[34:37], v[42:45], 0
	v_mfma_f32_16x16x32_bf16 v[30:33], v[30:33], v[58:61], v[34:37]
	v_mfma_f32_16x16x32_bf16 v[26:29], v[26:29], v[46:49], v[30:33]
	v_mfma_f32_16x16x32_bf16 v[22:25], v[22:25], v[66:69], v[26:29]
	v_mfma_f32_16x16x32_bf16 v[18:21], v[18:21], v[54:57], v[22:25]
	v_mfma_f32_16x16x32_bf16 v[14:17], v[14:17], v[62:65], v[18:21]
	v_mfma_f32_16x16x32_bf16 v[10:13], v[10:13], v[50:53], v[14:17]
	s_nop 5
	v_lshlrev_b32_e32 v18, 16, v207
	v_and_b32_e32 v19, 0xffff0000, v207
	ds_read_b128 v[14:17], v0 offset:65280
	v_mfma_f32_16x16x32_bf16 v[6:9], v[6:9], v[38:41], v[10:13]
	s_nop 2
	ds_read_b128 v[10:13], v0 offset:65344
	s_waitcnt lgkmcnt(1)
	v_mfma_f32_16x16x32_bf16 v[6:9], v[14:17], v[70:73], v[6:9]
	ds_read_b128 v[14:17], v0 offset:65408
	s_waitcnt lgkmcnt(1)
	v_mfma_f32_16x16x32_bf16 v[6:9], v[10:13], v[98:101], v[6:9]
	ds_read_b128 v[10:13], v0 offset:65472
	s_waitcnt lgkmcnt(1)
	v_mfma_f32_16x16x32_bf16 v[6:9], v[14:17], v[110:113], v[6:9]
	v_lshlrev_b32_e32 v14, 16, v206
	v_and_b32_e32 v15, 0xffff0000, v206
	s_waitcnt lgkmcnt(0)
	v_mfma_f32_16x16x32_bf16 v[6:9], v[10:13], v[114:117], v[6:9]
	s_nop 7
	v_pk_fma_f32 v[8:9], v[4:5], v[18:19], v[8:9]
	v_pk_fma_f32 v[6:7], v[2:3], v[14:15], v[6:7]
	v_mul_f32_e32 v10, 0x3d372713, v8
	v_mul_f32_e32 v11, 0x3d372713, v9
	v_mul_f32_e32 v12, 0x3d372713, v6
	v_mul_f32_e32 v13, 0x3d372713, v7
	v_mul_f32_e32 v10, v8, v10
	v_mul_f32_e32 v11, v9, v11
	v_mul_f32_e32 v12, v6, v12
	v_mul_f32_e32 v13, v7, v13
	v_fma_f32 v10, v8, v10, v8
	v_fma_f32 v11, v9, v11, v9
	v_fma_f32 v12, v6, v12, v6
	v_fma_f32 v13, v7, v13, v7
	v_mul_f32_e32 v10, 0x3f4c422a, v10
	v_mul_f32_e32 v11, 0x3f4c422a, v11
	v_mul_f32_e32 v12, 0x3f4c422a, v12
	v_mul_f32_e32 v13, 0x3f4c422a, v13
	v_add_f32_e32 v10, v10, v10
	v_add_f32_e32 v11, v11, v11
	v_add_f32_e32 v12, v12, v12
	v_add_f32_e32 v13, v13, v13
	v_mul_f32_e32 v10, 0xbfb8aa3b, v10
	v_mul_f32_e32 v11, 0xbfb8aa3b, v11
	v_mul_f32_e32 v12, 0xbfb8aa3b, v12
	v_mul_f32_e32 v13, 0xbfb8aa3b, v13
	v_exp_f32_e32 v10, v10
	v_exp_f32_e32 v11, v11
	v_exp_f32_e32 v12, v12
	v_exp_f32_e32 v13, v13
	v_add_f32_e32 v10, 1.0, v10
	v_add_f32_e32 v11, 1.0, v11
	v_add_f32_e32 v12, 1.0, v12
	v_add_f32_e32 v13, 1.0, v13
	v_rcp_f32_e32 v10, v10
	v_rcp_f32_e32 v11, v11
	v_rcp_f32_e32 v12, v12
	v_rcp_f32_e32 v13, v13
	v_pk_mul_f32 v[8:9], v[8:9], v[10:11]
	s_nop 0
	v_cvt_pk_bf16_f32 v9, v8, v9
	v_pk_mul_f32 v[6:7], v[6:7], v[12:13]
	s_nop 0
	v_cvt_pk_bf16_f32 v8, v6, v7
	v_mad_i64_i32 v[6:7], s[14:15], v148, s96, v[156:157]
	global_store_dwordx2 v[6:7], v[8:9], off
	s_branch .LBB0_525
